# P3 (LoRA-up) epilogue and prefix-product stores without the nontemporal hint (plain write-back stores)
# speedup vs baseline: 1.0201x; 1.0087x over previous
;     __device__ __forceinline__ void operator()(const f32x4 (&acc)[2][2][4][2], const Unit& u, int wr, int wc, int fr, int fq) const {
;         const int row0 = u.pm * BM + wr * 64 + fr, col0 = u.pn * BM + wc * 32 + 4 * fq;
; #pragma unroll
;         for (int bj = 0; bj < 2; ++bj)
; #pragma unroll
;             for (int n = 0; n < 2; ++n) { const f32x4 bv = *(const f32x4*)(bias + col0 + bj * HALF + n * 16);
; #pragma unroll
;                 for (int ai = 0; ai < 2; ++ai)
; #pragma unroll
;                     for (int m = 0; m < 4; ++m) { f32x4 v = acc[ai][bj][m][n] + bv, o;
; #pragma unroll
;                         for (int e = 0; e < 4; ++e) { const float z = v[e];
;                             const float sg = __builtin_amdgcn_rcpf(1.0f + __builtin_amdgcn_exp2f(-1.4426950408889634f * z));
;                             if (MODE == 0) o[e] = __builtin_amdgcn_exp2f(-0.8750387749f * sg);
;                             else o[e] = sg; }
;                         __builtin_nontemporal_store(o, (f32x4*)(O + (size_t)(row0 + ai * HALF + m * 16) * 1536 + col0 + bj * HALF + n * 16)); } }
.LBB0_378:
	s_load_dwordx16 s[40:55], s[62:63], 0x0
	v_lshl_or_b32 v100, s0, 8, v147
	v_ashrrev_i32_e32 v101, 31, v100
	v_lshlrev_b64 v[142:143], 2, v[100:101]
	v_lshl_add_u32 v153, s1, 8, v146
	s_waitcnt lgkmcnt(0)
	v_lshl_add_u64 v[140:141], s[50:51], 0, v[142:143]
	global_load_dwordx4 v[100:103], v[140:141], off
	global_load_dwordx4 v[212:215], v[140:141], off offset:64
	global_load_dwordx4 v[216:219], v[140:141], off offset:512
	global_load_dwordx4 v[220:223], v[140:141], off offset:576
	v_mov_b64_e32 v[144:145], s[8:9]
	v_mad_i64_i32 v[136:137], s[0:1], v153, s81, v[144:145]
	v_or_b32_e32 v138, 16, v153
	v_mad_i64_i32 v[138:139], s[0:1], v138, s81, v[144:145]
	v_lshl_add_u64 v[136:137], v[136:137], 0, v[142:143]
	v_lshl_add_u64 v[138:139], v[138:139], 0, v[142:143]
	v_or_b32_e32 v154, 32, v153
	s_andn2_b64 vcc, exec, s[22:23]
	s_mov_b64 s[22:23], -1
	s_waitcnt vmcnt(0)
	v_add_f32_e32 v120, v120, v100
	v_add_f32_e32 v121, v121, v101
	v_add_f32_e32 v122, v122, v102
	v_add_f32_e32 v123, v123, v103
	v_add_f32_e32 v124, v124, v100
	v_add_f32_e32 v125, v125, v101
	v_add_f32_e32 v126, v126, v102
	v_add_f32_e32 v127, v127, v103
	v_mul_f32_e32 v120, 0xbfb8aa3b, v120
	v_mul_f32_e32 v121, 0xbfb8aa3b, v121
	v_mul_f32_e32 v122, 0xbfb8aa3b, v122
	v_mul_f32_e32 v123, 0xbfb8aa3b, v123
	v_mul_f32_e32 v124, 0xbfb8aa3b, v124
	v_mul_f32_e32 v125, 0xbfb8aa3b, v125
	v_mul_f32_e32 v126, 0xbfb8aa3b, v126
	v_mul_f32_e32 v127, 0xbfb8aa3b, v127
	v_exp_f32_e32 v120, v120
	v_exp_f32_e32 v121, v121
	v_exp_f32_e32 v122, v122
	v_exp_f32_e32 v123, v123
	v_exp_f32_e32 v124, v124
	v_exp_f32_e32 v125, v125
	v_exp_f32_e32 v126, v126
	v_exp_f32_e32 v127, v127
	v_add_f32_e32 v112, v112, v100
	v_mul_f32_e32 v112, 0xbfb8aa3b, v112
	v_add_f32_e32 v120, 1.0, v120
	v_add_f32_e32 v121, 1.0, v121
	v_add_f32_e32 v122, 1.0, v122
	v_add_f32_e32 v123, 1.0, v123
	v_exp_f32_e32 v112, v112
	v_add_f32_e32 v124, 1.0, v124
	v_add_f32_e32 v125, 1.0, v125
	v_add_f32_e32 v126, 1.0, v126
	v_add_f32_e32 v127, 1.0, v127
	v_rcp_f32_e32 v120, v120
	v_rcp_f32_e32 v121, v121
	v_rcp_f32_e32 v122, v122
	v_rcp_f32_e32 v123, v123
	v_rcp_f32_e32 v124, v124
	v_rcp_f32_e32 v125, v125
	v_rcp_f32_e32 v126, v126
	v_rcp_f32_e32 v127, v127
	v_add_f32_e32 v112, 1.0, v112
	v_add_f32_e32 v113, v113, v101
	v_mul_f32_e32 v120, 0xbf60028b, v120
	v_mul_f32_e32 v121, 0xbf60028b, v121
	v_mul_f32_e32 v122, 0xbf60028b, v122
	v_mul_f32_e32 v123, 0xbf60028b, v123
	v_rcp_f32_e32 v112, v112
	v_mul_f32_e32 v113, 0xbfb8aa3b, v113
	v_mul_f32_e32 v124, 0xbf60028b, v124
	v_mul_f32_e32 v125, 0xbf60028b, v125
	v_mul_f32_e32 v126, 0xbf60028b, v126
	v_mul_f32_e32 v127, 0xbf60028b, v127
	v_exp_f32_e32 v120, v120
	v_exp_f32_e32 v121, v121
	v_exp_f32_e32 v122, v122
	v_exp_f32_e32 v123, v123
	v_exp_f32_e32 v113, v113
	v_exp_f32_e32 v124, v124
	v_exp_f32_e32 v125, v125
	v_exp_f32_e32 v126, v126
	v_exp_f32_e32 v127, v127
	v_mul_f32_e32 v112, 0xbf60028b, v112
	flat_store_dwordx4 v[136:137], v[120:123]
	flat_store_dwordx4 v[138:139], v[124:127]
	s_nop 0
	v_exp_f32_e32 v122, v112
	v_add_f32_e32 v112, 1.0, v113
	v_add_f32_e32 v113, v114, v102
	v_mul_f32_e32 v113, 0xbfb8aa3b, v113
	v_exp_f32_e32 v113, v113
	v_add_f32_e32 v114, v115, v103
	v_mul_f32_e32 v114, 0xbfb8aa3b, v114
	v_exp_f32_e32 v114, v114
	v_rcp_f32_e32 v112, v112
	v_add_f32_e32 v113, 1.0, v113
	v_rcp_f32_e32 v113, v113
	v_add_f32_e32 v114, 1.0, v114
	v_mul_f32_e32 v112, 0xbf60028b, v112
	v_rcp_f32_e32 v114, v114
	v_exp_f32_e32 v123, v112
	v_mul_f32_e32 v112, 0xbf60028b, v113
	v_add_f32_e32 v113, v116, v100
	v_mul_f32_e32 v113, 0xbfb8aa3b, v113
	v_exp_f32_e32 v116, v113
	v_exp_f32_e32 v124, v112
	v_mul_f32_e32 v112, 0xbf60028b, v114
	v_exp_f32_e32 v125, v112
	v_or_b32_e32 v112, 48, v153
	v_mad_i64_i32 v[112:113], s[0:1], v112, s81, v[144:145]
	v_lshl_add_u64 v[114:115], v[112:113], 0, v[142:143]
	v_add_f32_e32 v112, 1.0, v116
	v_add_f32_e32 v113, v117, v101
	v_rcp_f32_e32 v112, v112
	v_mul_f32_e32 v113, 0xbfb8aa3b, v113
	v_exp_f32_e32 v113, v113
	v_add_f32_e32 v117, v119, v103
	v_mul_f32_e32 v112, 0xbf60028b, v112
	v_exp_f32_e32 v116, v112
	v_add_f32_e32 v112, 1.0, v113
	v_add_f32_e32 v113, v118, v102
	v_mul_f32_e32 v113, 0xbfb8aa3b, v113
	v_exp_f32_e32 v113, v113
	v_mul_f32_e32 v117, 0xbfb8aa3b, v117
	v_exp_f32_e32 v117, v117
	v_add_f32_e32 v108, v108, v100
	v_rcp_f32_e32 v112, v112
	v_add_f32_e32 v113, 1.0, v113
	v_mul_f32_e32 v108, 0xbfb8aa3b, v108
	v_rcp_f32_e32 v113, v113
	v_add_f32_e32 v117, 1.0, v117
	v_exp_f32_e32 v108, v108
	v_rcp_f32_e32 v119, v117
	v_mul_f32_e32 v112, 0xbf60028b, v112
	v_exp_f32_e32 v117, v112
	v_mul_f32_e32 v112, 0xbf60028b, v113
	v_add_f32_e32 v108, 1.0, v108
	v_add_f32_e32 v109, v109, v101
	v_exp_f32_e32 v118, v112
	v_mul_f32_e32 v112, 0xbf60028b, v119
	v_rcp_f32_e32 v108, v108
	v_mul_f32_e32 v109, 0xbfb8aa3b, v109
	v_exp_f32_e32 v119, v112
	v_exp_f32_e32 v109, v109
	flat_store_dwordx4 v[114:115], v[122:125]
	v_mul_f32_e32 v108, 0xbf60028b, v108
	v_add_f32_e32 v104, v104, v100
	v_add_u32_e32 v122, 0x80, v153
	v_mad_i64_i32 v[112:113], s[0:1], v122, s81, v[144:145]
	v_lshl_add_u64 v[112:113], v[112:113], 0, v[142:143]
	flat_store_dwordx4 v[112:113], v[116:119]
	v_mul_f32_e32 v104, 0xbfb8aa3b, v104
	v_exp_f32_e32 v104, v104
	v_exp_f32_e32 v116, v108
	v_add_f32_e32 v108, 1.0, v109
	v_add_f32_e32 v109, v110, v102
	v_mul_f32_e32 v109, 0xbfb8aa3b, v109
	v_add_f32_e32 v110, v111, v103
	v_exp_f32_e32 v109, v109
	v_mul_f32_e32 v110, 0xbfb8aa3b, v110
	v_exp_f32_e32 v110, v110
	v_rcp_f32_e32 v108, v108
	v_add_f32_e32 v109, 1.0, v109
	v_rcp_f32_e32 v109, v109
	v_add_f32_e32 v110, 1.0, v110
	v_rcp_f32_e32 v110, v110
	v_mul_f32_e32 v108, 0xbf60028b, v108
;     __device__ __forceinline__ void operator()(const f32x4 (&acc)[2][2][4][2], const Unit& u, int wr, int wc, int fr, int fq) const {
;     ...
;         for (int bj = 0; bj < 2; ++bj)
; #pragma unroll
;             for (int n = 0; n < 2; ++n) { const f32x4 bv = *(const f32x4*)(bias + col0 + bj * HALF + n * 16);
; #pragma unroll
;                 for (int ai = 0; ai < 2; ++ai)
; #pragma unroll
;                     for (int m = 0; m < 4; ++m) { f32x4 v = acc[ai][bj][m][n] + bv, o;
; #pragma unroll
;                         for (int e = 0; e < 4; ++e) { const float z = v[e];
;                             const float sg = __builtin_amdgcn_rcpf(1.0f + __builtin_amdgcn_exp2f(-1.4426950408889634f * z));
;                             if (MODE == 0) o[e] = __builtin_amdgcn_exp2f(-0.8750387749f * sg);
;                             else o[e] = sg; }
;                         __builtin_nontemporal_store(o, (f32x4*)(O + (size_t)(row0 + ai * HALF + m * 16) * 1536 + col0 + bj * HALF + n * 16)); } }
	v_exp_f32_e32 v117, v108
	v_mul_f32_e32 v108, 0xbf60028b, v109
	v_add_f32_e32 v104, 1.0, v104
	v_add_f32_e32 v105, v105, v101
	v_exp_f32_e32 v118, v108
	v_mul_f32_e32 v108, 0xbf60028b, v110
	v_rcp_f32_e32 v104, v104
	v_mul_f32_e32 v105, 0xbfb8aa3b, v105
	v_exp_f32_e32 v119, v108
	v_exp_f32_e32 v105, v105
	v_add_u32_e32 v108, 0x90, v153
	v_mad_i64_i32 v[108:109], s[0:1], v108, s81, v[144:145]
	v_lshl_add_u64 v[108:109], v[108:109], 0, v[142:143]
	v_mul_f32_e32 v104, 0xbf60028b, v104
	flat_store_dwordx4 v[108:109], v[116:119]
	v_add_f32_e32 v128, v128, v100
	v_add_f32_e32 v129, v129, v101
	v_exp_f32_e32 v116, v104
	v_add_f32_e32 v104, 1.0, v105
	v_add_f32_e32 v105, v106, v102
	v_add_f32_e32 v130, v130, v102
	v_add_f32_e32 v131, v131, v103
	v_mul_f32_e32 v105, 0xbfb8aa3b, v105
	v_add_f32_e32 v106, v107, v103
	v_add_f32_e32 v96, v96, v100
	v_add_f32_e32 v97, v97, v101
	v_add_f32_e32 v98, v98, v102
	v_add_f32_e32 v99, v99, v103
	v_mul_f32_e32 v128, 0xbfb8aa3b, v128
	v_mul_f32_e32 v129, 0xbfb8aa3b, v129
	v_mul_f32_e32 v130, 0xbfb8aa3b, v130
	v_mul_f32_e32 v131, 0xbfb8aa3b, v131
	v_exp_f32_e32 v105, v105
	v_mul_f32_e32 v106, 0xbfb8aa3b, v106
	v_mul_f32_e32 v96, 0xbfb8aa3b, v96
	v_mul_f32_e32 v97, 0xbfb8aa3b, v97
	v_mul_f32_e32 v98, 0xbfb8aa3b, v98
	v_mul_f32_e32 v99, 0xbfb8aa3b, v99
	v_exp_f32_e32 v128, v128
	v_exp_f32_e32 v129, v129
	v_exp_f32_e32 v130, v130
	v_exp_f32_e32 v131, v131
	v_exp_f32_e32 v106, v106
	v_exp_f32_e32 v96, v96
	v_exp_f32_e32 v97, v97
	v_exp_f32_e32 v98, v98
	v_exp_f32_e32 v99, v99
	v_rcp_f32_e32 v104, v104
	v_add_f32_e32 v105, 1.0, v105
	v_add_f32_e32 v128, 1.0, v128
	v_add_f32_e32 v129, 1.0, v129
	v_add_f32_e32 v130, 1.0, v130
	v_add_f32_e32 v131, 1.0, v131
	v_rcp_f32_e32 v105, v105
	v_add_f32_e32 v106, 1.0, v106
	v_add_f32_e32 v96, 1.0, v96
	v_add_f32_e32 v97, 1.0, v97
	v_add_f32_e32 v98, 1.0, v98
	v_add_f32_e32 v99, 1.0, v99
	v_rcp_f32_e32 v128, v128
	v_rcp_f32_e32 v129, v129
	v_rcp_f32_e32 v130, v130
	v_rcp_f32_e32 v131, v131
	v_rcp_f32_e32 v106, v106
	v_rcp_f32_e32 v96, v96
	v_rcp_f32_e32 v97, v97
	v_rcp_f32_e32 v98, v98
	v_rcp_f32_e32 v99, v99
	v_mul_f32_e32 v104, 0xbf60028b, v104
	v_exp_f32_e32 v117, v104
	v_mul_f32_e32 v104, 0xbf60028b, v105
	v_mul_f32_e32 v128, 0xbf60028b, v128
	v_mul_f32_e32 v129, 0xbf60028b, v129
	v_mul_f32_e32 v130, 0xbf60028b, v130
	v_mul_f32_e32 v131, 0xbf60028b, v131
	v_exp_f32_e32 v118, v104
	v_mul_f32_e32 v104, 0xbf60028b, v106
	v_mul_f32_e32 v96, 0xbf60028b, v96
	v_mul_f32_e32 v97, 0xbf60028b, v97
	v_mul_f32_e32 v98, 0xbf60028b, v98
	v_mul_f32_e32 v99, 0xbf60028b, v99
	v_exp_f32_e32 v128, v128
	v_exp_f32_e32 v129, v129
	v_exp_f32_e32 v130, v130
	v_exp_f32_e32 v131, v131
	v_exp_f32_e32 v119, v104
	v_exp_f32_e32 v96, v96
	v_exp_f32_e32 v97, v97
	v_exp_f32_e32 v98, v98
	v_exp_f32_e32 v99, v99
	v_add_u32_e32 v104, 0xa0, v153
	v_add_u32_e32 v100, 0xb0, v153
	v_mad_i64_i32 v[120:121], s[0:1], v154, s81, v[144:145]
	v_mad_i64_i32 v[104:105], s[0:1], v104, s81, v[144:145]
	v_mad_i64_i32 v[100:101], s[0:1], v100, s81, v[144:145]
	v_lshl_add_u64 v[120:121], v[120:121], 0, v[142:143]
	v_lshl_add_u64 v[104:105], v[104:105], 0, v[142:143]
	v_lshl_add_u64 v[100:101], v[100:101], 0, v[142:143]
	flat_store_dwordx4 v[120:121], v[128:131]
	flat_store_dwordx4 v[104:105], v[116:119]
	flat_store_dwordx4 v[100:101], v[96:99]
	s_nop 3
	v_mov_b64_e32 v[96:97], v[212:213]
	v_mov_b64_e32 v[98:99], v[214:215]
	v_add_f32_e32 v92, v92, v96
	v_add_f32_e32 v93, v93, v97
	v_add_f32_e32 v94, v94, v98
	v_add_f32_e32 v95, v95, v99
	v_add_f32_e32 v76, v76, v96
	v_add_f32_e32 v77, v77, v97
	v_add_f32_e32 v78, v78, v98
	v_add_f32_e32 v79, v79, v99
	v_mul_f32_e32 v92, 0xbfb8aa3b, v92
	v_mul_f32_e32 v93, 0xbfb8aa3b, v93
	v_mul_f32_e32 v94, 0xbfb8aa3b, v94
	v_mul_f32_e32 v95, 0xbfb8aa3b, v95
	v_add_f32_e32 v88, v88, v96
	v_add_f32_e32 v89, v89, v97
	v_add_f32_e32 v90, v90, v98
	v_add_f32_e32 v91, v91, v99
	v_mul_f32_e32 v76, 0xbfb8aa3b, v76
	v_mul_f32_e32 v77, 0xbfb8aa3b, v77
	v_mul_f32_e32 v78, 0xbfb8aa3b, v78
	v_mul_f32_e32 v79, 0xbfb8aa3b, v79
	v_exp_f32_e32 v92, v92
	v_exp_f32_e32 v93, v93
	v_exp_f32_e32 v94, v94
	v_exp_f32_e32 v95, v95
	v_mul_f32_e32 v88, 0xbfb8aa3b, v88
	v_mul_f32_e32 v89, 0xbfb8aa3b, v89
	v_mul_f32_e32 v90, 0xbfb8aa3b, v90
	v_mul_f32_e32 v91, 0xbfb8aa3b, v91
	v_add_f32_e32 v84, v84, v96
	v_add_f32_e32 v85, v85, v97
	v_add_f32_e32 v86, v86, v98
	v_add_f32_e32 v87, v87, v99
	v_exp_f32_e32 v76, v76
	v_exp_f32_e32 v77, v77
	v_exp_f32_e32 v78, v78
	v_exp_f32_e32 v79, v79
	v_exp_f32_e32 v88, v88
	v_exp_f32_e32 v89, v89
	v_exp_f32_e32 v90, v90
	v_exp_f32_e32 v91, v91
	v_mul_f32_e32 v84, 0xbfb8aa3b, v84
	v_mul_f32_e32 v85, 0xbfb8aa3b, v85
	v_mul_f32_e32 v86, 0xbfb8aa3b, v86
	v_mul_f32_e32 v87, 0xbfb8aa3b, v87
	v_exp_f32_e32 v84, v84
	v_exp_f32_e32 v85, v85
	v_exp_f32_e32 v86, v86
	v_exp_f32_e32 v87, v87
	v_add_f32_e32 v92, 1.0, v92
	v_add_f32_e32 v93, 1.0, v93
	v_add_f32_e32 v94, 1.0, v94
	v_add_f32_e32 v95, 1.0, v95
	v_add_f32_e32 v76, 1.0, v76
	v_add_f32_e32 v77, 1.0, v77
	v_add_f32_e32 v78, 1.0, v78
	v_add_f32_e32 v79, 1.0, v79
	v_rcp_f32_e32 v92, v92
	v_rcp_f32_e32 v93, v93
	v_rcp_f32_e32 v94, v94
	v_rcp_f32_e32 v95, v95
	v_add_f32_e32 v88, 1.0, v88
	v_add_f32_e32 v89, 1.0, v89
	v_add_f32_e32 v90, 1.0, v90
	v_add_f32_e32 v91, 1.0, v91
	v_rcp_f32_e32 v76, v76
	v_rcp_f32_e32 v77, v77
	v_rcp_f32_e32 v78, v78
	v_rcp_f32_e32 v79, v79
	v_rcp_f32_e32 v88, v88
	v_rcp_f32_e32 v89, v89
	v_rcp_f32_e32 v90, v90
	v_rcp_f32_e32 v91, v91
	v_add_f32_e32 v84, 1.0, v84
	v_add_f32_e32 v85, 1.0, v85
	v_add_f32_e32 v86, 1.0, v86
	v_add_f32_e32 v87, 1.0, v87
	v_rcp_f32_e32 v84, v84
	v_rcp_f32_e32 v85, v85
	v_rcp_f32_e32 v86, v86
;     __device__ __forceinline__ void operator()(const f32x4 (&acc)[2][2][4][2], const Unit& u, int wr, int wc, int fr, int fq) const {
;     ...
;         for (int bj = 0; bj < 2; ++bj)
; #pragma unroll
;             for (int n = 0; n < 2; ++n) { const f32x4 bv = *(const f32x4*)(bias + col0 + bj * HALF + n * 16);
; #pragma unroll
;                 for (int ai = 0; ai < 2; ++ai)
; #pragma unroll
;                     for (int m = 0; m < 4; ++m) { f32x4 v = acc[ai][bj][m][n] + bv, o;
; #pragma unroll
;                         for (int e = 0; e < 4; ++e) { const float z = v[e];
;                             const float sg = __builtin_amdgcn_rcpf(1.0f + __builtin_amdgcn_exp2f(-1.4426950408889634f * z));
;                             if (MODE == 0) o[e] = __builtin_amdgcn_exp2f(-0.8750387749f * sg);
;                             else o[e] = sg; }
;                         __builtin_nontemporal_store(o, (f32x4*)(O + (size_t)(row0 + ai * HALF + m * 16) * 1536 + col0 + bj * HALF + n * 16)); } }
	v_rcp_f32_e32 v87, v87
	v_mul_f32_e32 v92, 0xbf60028b, v92
	v_mul_f32_e32 v93, 0xbf60028b, v93
	v_mul_f32_e32 v94, 0xbf60028b, v94
	v_mul_f32_e32 v95, 0xbf60028b, v95
	v_mul_f32_e32 v76, 0xbf60028b, v76
	v_mul_f32_e32 v77, 0xbf60028b, v77
	v_mul_f32_e32 v78, 0xbf60028b, v78
	v_mul_f32_e32 v79, 0xbf60028b, v79
	v_exp_f32_e32 v92, v92
	v_exp_f32_e32 v93, v93
	v_exp_f32_e32 v94, v94
	v_exp_f32_e32 v95, v95
	v_mul_f32_e32 v88, 0xbf60028b, v88
	v_mul_f32_e32 v89, 0xbf60028b, v89
	v_mul_f32_e32 v90, 0xbf60028b, v90
	v_mul_f32_e32 v91, 0xbf60028b, v91
	v_exp_f32_e32 v76, v76
	v_exp_f32_e32 v77, v77
	v_exp_f32_e32 v78, v78
	v_exp_f32_e32 v79, v79
	v_exp_f32_e32 v88, v88
	v_exp_f32_e32 v89, v89
	v_exp_f32_e32 v90, v90
	v_exp_f32_e32 v91, v91
	v_mul_f32_e32 v84, 0xbf60028b, v84
	v_mul_f32_e32 v85, 0xbf60028b, v85
	v_mul_f32_e32 v86, 0xbf60028b, v86
	v_mul_f32_e32 v87, 0xbf60028b, v87
	v_exp_f32_e32 v84, v84
	v_exp_f32_e32 v85, v85
	v_exp_f32_e32 v86, v86
	v_exp_f32_e32 v87, v87
	flat_store_dwordx4 v[136:137], v[92:95] offset:64
	flat_store_dwordx4 v[138:139], v[88:91] offset:64
	flat_store_dwordx4 v[120:121], v[84:87] offset:64
	v_add_f32_e32 v80, v80, v96
	v_add_f32_e32 v81, v81, v97
	flat_store_dwordx4 v[114:115], v[76:79] offset:64
	v_mul_f32_e32 v80, 0xbfb8aa3b, v80
	v_mul_f32_e32 v81, 0xbfb8aa3b, v81
	v_add_f32_e32 v78, v82, v98
	v_add_f32_e32 v79, v83, v99
	v_mul_f32_e32 v78, 0xbfb8aa3b, v78
	v_mul_f32_e32 v79, 0xbfb8aa3b, v79
	v_add_f32_e32 v72, v72, v96
	v_add_f32_e32 v73, v73, v97
	v_add_f32_e32 v74, v74, v98
	v_add_f32_e32 v75, v75, v99
	v_exp_f32_e32 v80, v80
	v_exp_f32_e32 v81, v81
	v_exp_f32_e32 v78, v78
	v_exp_f32_e32 v79, v79
	v_mul_f32_e32 v72, 0xbfb8aa3b, v72
	v_mul_f32_e32 v73, 0xbfb8aa3b, v73
	v_mul_f32_e32 v74, 0xbfb8aa3b, v74
	v_mul_f32_e32 v75, 0xbfb8aa3b, v75
	v_add_f32_e32 v68, v68, v96
	v_add_f32_e32 v69, v69, v97
	v_add_f32_e32 v70, v70, v98
	v_add_f32_e32 v71, v71, v99
	v_exp_f32_e32 v72, v72
	v_exp_f32_e32 v73, v73
	v_exp_f32_e32 v74, v74
	v_exp_f32_e32 v75, v75
	v_mul_f32_e32 v68, 0xbfb8aa3b, v68
	v_mul_f32_e32 v69, 0xbfb8aa3b, v69
	v_mul_f32_e32 v70, 0xbfb8aa3b, v70
	v_mul_f32_e32 v71, 0xbfb8aa3b, v71
	v_add_f32_e32 v64, v64, v96
	v_add_f32_e32 v65, v65, v97
	v_add_f32_e32 v66, v66, v98
	v_add_f32_e32 v67, v67, v99
	v_exp_f32_e32 v68, v68
	v_exp_f32_e32 v69, v69
	v_exp_f32_e32 v70, v70
	v_exp_f32_e32 v71, v71
	v_mul_f32_e32 v64, 0xbfb8aa3b, v64
	v_mul_f32_e32 v65, 0xbfb8aa3b, v65
	v_mul_f32_e32 v66, 0xbfb8aa3b, v66
	v_mul_f32_e32 v67, 0xbfb8aa3b, v67
	v_exp_f32_e32 v64, v64
	v_exp_f32_e32 v65, v65
	v_exp_f32_e32 v66, v66
	v_exp_f32_e32 v67, v67
	v_add_f32_e32 v80, 1.0, v80
	v_add_f32_e32 v77, 1.0, v81
	v_add_f32_e32 v78, 1.0, v78
	v_add_f32_e32 v79, 1.0, v79
	v_rcp_f32_e32 v80, v80
	v_rcp_f32_e32 v77, v77
	v_rcp_f32_e32 v78, v78
	v_rcp_f32_e32 v79, v79
	v_add_f32_e32 v72, 1.0, v72
	v_add_f32_e32 v73, 1.0, v73
	v_add_f32_e32 v74, 1.0, v74
	v_add_f32_e32 v75, 1.0, v75
	v_rcp_f32_e32 v72, v72
	v_rcp_f32_e32 v73, v73
	v_rcp_f32_e32 v74, v74
	v_rcp_f32_e32 v75, v75
	v_add_f32_e32 v68, 1.0, v68
	v_add_f32_e32 v69, 1.0, v69
	v_add_f32_e32 v70, 1.0, v70
	v_add_f32_e32 v71, 1.0, v71
	v_rcp_f32_e32 v68, v68
	v_rcp_f32_e32 v69, v69
	v_rcp_f32_e32 v70, v70
	v_rcp_f32_e32 v71, v71
	v_add_f32_e32 v64, 1.0, v64
	v_add_f32_e32 v65, 1.0, v65
	v_add_f32_e32 v66, 1.0, v66
	v_add_f32_e32 v67, 1.0, v67
	v_rcp_f32_e32 v64, v64
	v_rcp_f32_e32 v65, v65
	v_rcp_f32_e32 v66, v66
	v_rcp_f32_e32 v67, v67
	v_mul_f32_e32 v76, 0xbf60028b, v80
	v_mul_f32_e32 v77, 0xbf60028b, v77
	v_mul_f32_e32 v78, 0xbf60028b, v78
	v_mul_f32_e32 v79, 0xbf60028b, v79
	v_exp_f32_e32 v76, v76
	v_exp_f32_e32 v77, v77
	v_exp_f32_e32 v78, v78
	v_exp_f32_e32 v79, v79
	v_mul_f32_e32 v72, 0xbf60028b, v72
	v_mul_f32_e32 v73, 0xbf60028b, v73
	v_mul_f32_e32 v74, 0xbf60028b, v74
	v_mul_f32_e32 v75, 0xbf60028b, v75
	v_exp_f32_e32 v72, v72
	v_exp_f32_e32 v73, v73
	v_exp_f32_e32 v74, v74
	v_exp_f32_e32 v75, v75
	v_mul_f32_e32 v68, 0xbf60028b, v68
	v_mul_f32_e32 v69, 0xbf60028b, v69
	v_mul_f32_e32 v70, 0xbf60028b, v70
	v_mul_f32_e32 v71, 0xbf60028b, v71
	v_exp_f32_e32 v68, v68
	v_exp_f32_e32 v69, v69
	v_exp_f32_e32 v70, v70
	v_exp_f32_e32 v71, v71
	v_mul_f32_e32 v64, 0xbf60028b, v64
	v_mul_f32_e32 v65, 0xbf60028b, v65
	v_mul_f32_e32 v66, 0xbf60028b, v66
	v_mul_f32_e32 v67, 0xbf60028b, v67
	v_exp_f32_e32 v64, v64
	v_exp_f32_e32 v65, v65
	v_exp_f32_e32 v66, v66
	v_exp_f32_e32 v67, v67
	flat_store_dwordx4 v[112:113], v[76:79] offset:64
	flat_store_dwordx4 v[108:109], v[72:75] offset:64
	flat_store_dwordx4 v[104:105], v[68:71] offset:64
	flat_store_dwordx4 v[100:101], v[64:67] offset:64
	s_nop 3
	v_mov_b64_e32 v[64:65], v[216:217]
	v_mov_b64_e32 v[66:67], v[218:219]
	v_add_f32_e32 v60, v60, v64
	v_add_f32_e32 v61, v61, v65
	v_add_f32_e32 v62, v62, v66
	v_add_f32_e32 v63, v63, v67
	v_add_f32_e32 v44, v44, v64
	v_add_f32_e32 v45, v45, v65
	v_add_f32_e32 v46, v46, v66
	v_add_f32_e32 v47, v47, v67
	v_mul_f32_e32 v60, 0xbfb8aa3b, v60
	v_mul_f32_e32 v61, 0xbfb8aa3b, v61
	v_mul_f32_e32 v62, 0xbfb8aa3b, v62
	v_mul_f32_e32 v63, 0xbfb8aa3b, v63
	v_add_f32_e32 v56, v56, v64
	v_add_f32_e32 v57, v57, v65
	v_add_f32_e32 v58, v58, v66
	v_add_f32_e32 v59, v59, v67
	v_mul_f32_e32 v44, 0xbfb8aa3b, v44
	v_mul_f32_e32 v45, 0xbfb8aa3b, v45
	v_mul_f32_e32 v46, 0xbfb8aa3b, v46
	v_mul_f32_e32 v47, 0xbfb8aa3b, v47
	v_exp_f32_e32 v60, v60
	v_exp_f32_e32 v61, v61
	v_exp_f32_e32 v62, v62
	v_exp_f32_e32 v63, v63
	v_mul_f32_e32 v56, 0xbfb8aa3b, v56
	v_mul_f32_e32 v57, 0xbfb8aa3b, v57
	v_mul_f32_e32 v58, 0xbfb8aa3b, v58
	v_mul_f32_e32 v59, 0xbfb8aa3b, v59
	v_add_f32_e32 v52, v52, v64
	v_add_f32_e32 v53, v53, v65
;     __device__ __forceinline__ void operator()(const f32x4 (&acc)[2][2][4][2], const Unit& u, int wr, int wc, int fr, int fq) const {
;     ...
;         for (int bj = 0; bj < 2; ++bj)
; #pragma unroll
;             for (int n = 0; n < 2; ++n) { const f32x4 bv = *(const f32x4*)(bias + col0 + bj * HALF + n * 16);
; #pragma unroll
;                 for (int ai = 0; ai < 2; ++ai)
; #pragma unroll
;                     for (int m = 0; m < 4; ++m) { f32x4 v = acc[ai][bj][m][n] + bv, o;
; #pragma unroll
;                         for (int e = 0; e < 4; ++e) { const float z = v[e];
;                             const float sg = __builtin_amdgcn_rcpf(1.0f + __builtin_amdgcn_exp2f(-1.4426950408889634f * z));
;                             if (MODE == 0) o[e] = __builtin_amdgcn_exp2f(-0.8750387749f * sg);
;                             else o[e] = sg; }
;                         __builtin_nontemporal_store(o, (f32x4*)(O + (size_t)(row0 + ai * HALF + m * 16) * 1536 + col0 + bj * HALF + n * 16)); } }
	v_add_f32_e32 v54, v54, v66
	v_add_f32_e32 v55, v55, v67
	v_exp_f32_e32 v44, v44
	v_exp_f32_e32 v45, v45
	v_exp_f32_e32 v46, v46
	v_exp_f32_e32 v47, v47
	v_exp_f32_e32 v56, v56
	v_exp_f32_e32 v57, v57
	v_exp_f32_e32 v58, v58
	v_exp_f32_e32 v59, v59
	v_mul_f32_e32 v52, 0xbfb8aa3b, v52
	v_mul_f32_e32 v53, 0xbfb8aa3b, v53
	v_mul_f32_e32 v54, 0xbfb8aa3b, v54
	v_mul_f32_e32 v55, 0xbfb8aa3b, v55
	v_exp_f32_e32 v52, v52
	v_exp_f32_e32 v53, v53
	v_exp_f32_e32 v54, v54
	v_exp_f32_e32 v55, v55
	v_add_f32_e32 v60, 1.0, v60
	v_add_f32_e32 v61, 1.0, v61
	v_add_f32_e32 v62, 1.0, v62
	v_add_f32_e32 v63, 1.0, v63
	v_add_f32_e32 v44, 1.0, v44
	v_add_f32_e32 v45, 1.0, v45
	v_add_f32_e32 v46, 1.0, v46
	v_add_f32_e32 v47, 1.0, v47
	v_rcp_f32_e32 v60, v60
	v_rcp_f32_e32 v61, v61
	v_rcp_f32_e32 v62, v62
	v_rcp_f32_e32 v63, v63
	v_add_f32_e32 v56, 1.0, v56
	v_add_f32_e32 v57, 1.0, v57
	v_add_f32_e32 v58, 1.0, v58
	v_add_f32_e32 v59, 1.0, v59
	v_rcp_f32_e32 v44, v44
	v_rcp_f32_e32 v45, v45
	v_rcp_f32_e32 v46, v46
	v_rcp_f32_e32 v47, v47
	v_rcp_f32_e32 v56, v56
	v_rcp_f32_e32 v57, v57
	v_rcp_f32_e32 v58, v58
	v_rcp_f32_e32 v59, v59
	v_add_f32_e32 v52, 1.0, v52
	v_add_f32_e32 v53, 1.0, v53
	v_add_f32_e32 v54, 1.0, v54
	v_add_f32_e32 v55, 1.0, v55
	v_rcp_f32_e32 v52, v52
	v_rcp_f32_e32 v53, v53
	v_rcp_f32_e32 v54, v54
	v_rcp_f32_e32 v55, v55
	v_mul_f32_e32 v60, 0xbf60028b, v60
	v_mul_f32_e32 v61, 0xbf60028b, v61
	v_mul_f32_e32 v62, 0xbf60028b, v62
	v_mul_f32_e32 v63, 0xbf60028b, v63
	v_mul_f32_e32 v44, 0xbf60028b, v44
	v_mul_f32_e32 v45, 0xbf60028b, v45
	v_mul_f32_e32 v46, 0xbf60028b, v46
	v_mul_f32_e32 v47, 0xbf60028b, v47
	v_exp_f32_e32 v60, v60
	v_exp_f32_e32 v61, v61
	v_exp_f32_e32 v62, v62
	v_exp_f32_e32 v63, v63
	v_mul_f32_e32 v56, 0xbf60028b, v56
	v_mul_f32_e32 v57, 0xbf60028b, v57
	v_mul_f32_e32 v58, 0xbf60028b, v58
	v_mul_f32_e32 v59, 0xbf60028b, v59
	v_exp_f32_e32 v44, v44
	v_exp_f32_e32 v45, v45
	v_exp_f32_e32 v46, v46
	v_exp_f32_e32 v47, v47
	v_exp_f32_e32 v56, v56
	v_exp_f32_e32 v57, v57
	v_exp_f32_e32 v58, v58
	v_exp_f32_e32 v59, v59
	v_mul_f32_e32 v52, 0xbf60028b, v52
	v_mul_f32_e32 v53, 0xbf60028b, v53
	v_mul_f32_e32 v54, 0xbf60028b, v54
	v_mul_f32_e32 v55, 0xbf60028b, v55
	v_exp_f32_e32 v52, v52
	v_exp_f32_e32 v53, v53
	v_exp_f32_e32 v54, v54
	v_exp_f32_e32 v55, v55
	flat_store_dwordx4 v[136:137], v[60:63] offset:512
	flat_store_dwordx4 v[138:139], v[56:59] offset:512
	flat_store_dwordx4 v[120:121], v[52:55] offset:512
	v_add_f32_e32 v48, v48, v64
	v_add_f32_e32 v49, v49, v65
	flat_store_dwordx4 v[114:115], v[44:47] offset:512
	v_mul_f32_e32 v48, 0xbfb8aa3b, v48
	v_mul_f32_e32 v49, 0xbfb8aa3b, v49
	v_add_f32_e32 v46, v50, v66
	v_add_f32_e32 v47, v51, v67
	v_mul_f32_e32 v46, 0xbfb8aa3b, v46
	v_mul_f32_e32 v47, 0xbfb8aa3b, v47
	v_add_f32_e32 v40, v40, v64
	v_add_f32_e32 v41, v41, v65
	v_add_f32_e32 v42, v42, v66
	v_add_f32_e32 v43, v43, v67
	v_exp_f32_e32 v48, v48
	v_exp_f32_e32 v49, v49
	v_exp_f32_e32 v46, v46
	v_exp_f32_e32 v47, v47
	v_mul_f32_e32 v40, 0xbfb8aa3b, v40
	v_mul_f32_e32 v41, 0xbfb8aa3b, v41
	v_mul_f32_e32 v42, 0xbfb8aa3b, v42
	v_mul_f32_e32 v43, 0xbfb8aa3b, v43
	v_add_f32_e32 v36, v36, v64
	v_add_f32_e32 v37, v37, v65
	v_add_f32_e32 v38, v38, v66
	v_add_f32_e32 v39, v39, v67
	v_exp_f32_e32 v40, v40
	v_exp_f32_e32 v41, v41
	v_exp_f32_e32 v42, v42
	v_exp_f32_e32 v43, v43
	v_mul_f32_e32 v36, 0xbfb8aa3b, v36
	v_mul_f32_e32 v37, 0xbfb8aa3b, v37
	v_mul_f32_e32 v38, 0xbfb8aa3b, v38
	v_mul_f32_e32 v39, 0xbfb8aa3b, v39
	v_add_f32_e32 v32, v32, v64
	v_add_f32_e32 v33, v33, v65
	v_add_f32_e32 v34, v34, v66
	v_add_f32_e32 v35, v35, v67
	v_exp_f32_e32 v36, v36
	v_exp_f32_e32 v37, v37
	v_exp_f32_e32 v38, v38
	v_exp_f32_e32 v39, v39
	v_mul_f32_e32 v32, 0xbfb8aa3b, v32
	v_mul_f32_e32 v33, 0xbfb8aa3b, v33
	v_mul_f32_e32 v34, 0xbfb8aa3b, v34
	v_mul_f32_e32 v35, 0xbfb8aa3b, v35
	v_exp_f32_e32 v32, v32
	v_exp_f32_e32 v33, v33
	v_exp_f32_e32 v34, v34
	v_exp_f32_e32 v35, v35
	v_add_f32_e32 v48, 1.0, v48
	v_add_f32_e32 v45, 1.0, v49
	v_add_f32_e32 v46, 1.0, v46
	v_add_f32_e32 v47, 1.0, v47
	v_rcp_f32_e32 v48, v48
	v_rcp_f32_e32 v45, v45
	v_rcp_f32_e32 v46, v46
	v_rcp_f32_e32 v47, v47
	v_add_f32_e32 v40, 1.0, v40
	v_add_f32_e32 v41, 1.0, v41
	v_add_f32_e32 v42, 1.0, v42
	v_add_f32_e32 v43, 1.0, v43
	v_rcp_f32_e32 v40, v40
	v_rcp_f32_e32 v41, v41
	v_rcp_f32_e32 v42, v42
	v_rcp_f32_e32 v43, v43
	v_add_f32_e32 v36, 1.0, v36
	v_add_f32_e32 v37, 1.0, v37
	v_add_f32_e32 v38, 1.0, v38
	v_add_f32_e32 v39, 1.0, v39
	v_rcp_f32_e32 v36, v36
	v_rcp_f32_e32 v37, v37
	v_rcp_f32_e32 v38, v38
	v_rcp_f32_e32 v39, v39
	v_add_f32_e32 v32, 1.0, v32
	v_add_f32_e32 v33, 1.0, v33
	v_add_f32_e32 v34, 1.0, v34
	v_add_f32_e32 v35, 1.0, v35
	v_rcp_f32_e32 v32, v32
	v_rcp_f32_e32 v33, v33
	v_rcp_f32_e32 v34, v34
	v_rcp_f32_e32 v35, v35
	v_mul_f32_e32 v44, 0xbf60028b, v48
	v_mul_f32_e32 v45, 0xbf60028b, v45
	v_mul_f32_e32 v46, 0xbf60028b, v46
	v_mul_f32_e32 v47, 0xbf60028b, v47
	v_exp_f32_e32 v44, v44
	v_exp_f32_e32 v45, v45
	v_exp_f32_e32 v46, v46
	v_exp_f32_e32 v47, v47
	v_mul_f32_e32 v40, 0xbf60028b, v40
	v_mul_f32_e32 v41, 0xbf60028b, v41
	v_mul_f32_e32 v42, 0xbf60028b, v42
	v_mul_f32_e32 v43, 0xbf60028b, v43
	v_exp_f32_e32 v40, v40
	v_exp_f32_e32 v41, v41
	v_exp_f32_e32 v42, v42
	v_exp_f32_e32 v43, v43
	v_mul_f32_e32 v36, 0xbf60028b, v36
	v_mul_f32_e32 v37, 0xbf60028b, v37
	v_mul_f32_e32 v38, 0xbf60028b, v38
	v_mul_f32_e32 v39, 0xbf60028b, v39
	v_exp_f32_e32 v36, v36
	v_exp_f32_e32 v37, v37
	v_exp_f32_e32 v38, v38
	v_exp_f32_e32 v39, v39
	v_mul_f32_e32 v32, 0xbf60028b, v32
	v_mul_f32_e32 v33, 0xbf60028b, v33
	v_mul_f32_e32 v34, 0xbf60028b, v34
	v_mul_f32_e32 v35, 0xbf60028b, v35
;     __device__ __forceinline__ void operator()(const f32x4 (&acc)[2][2][4][2], const Unit& u, int wr, int wc, int fr, int fq) const {
;     ...
;         for (int bj = 0; bj < 2; ++bj)
; #pragma unroll
;             for (int n = 0; n < 2; ++n) { const f32x4 bv = *(const f32x4*)(bias + col0 + bj * HALF + n * 16);
; #pragma unroll
;                 for (int ai = 0; ai < 2; ++ai)
; #pragma unroll
;                     for (int m = 0; m < 4; ++m) { f32x4 v = acc[ai][bj][m][n] + bv, o;
; #pragma unroll
;                         for (int e = 0; e < 4; ++e) { const float z = v[e];
;                             const float sg = __builtin_amdgcn_rcpf(1.0f + __builtin_amdgcn_exp2f(-1.4426950408889634f * z));
;                             if (MODE == 0) o[e] = __builtin_amdgcn_exp2f(-0.8750387749f * sg);
;                             else o[e] = sg; }
;                         __builtin_nontemporal_store(o, (f32x4*)(O + (size_t)(row0 + ai * HALF + m * 16) * 1536 + col0 + bj * HALF + n * 16)); } }
	v_exp_f32_e32 v32, v32
	v_exp_f32_e32 v33, v33
	v_exp_f32_e32 v34, v34
	v_exp_f32_e32 v35, v35
	flat_store_dwordx4 v[112:113], v[44:47] offset:512
	flat_store_dwordx4 v[108:109], v[40:43] offset:512
	flat_store_dwordx4 v[104:105], v[36:39] offset:512
	flat_store_dwordx4 v[100:101], v[32:35] offset:512
	s_nop 3
	v_mov_b64_e32 v[32:33], v[220:221]
	v_mov_b64_e32 v[34:35], v[222:223]
	v_add_f32_e32 v28, v28, v32
	v_add_f32_e32 v29, v29, v33
	v_add_f32_e32 v30, v30, v34
	v_add_f32_e32 v31, v31, v35
	v_add_f32_e32 v12, v12, v32
	v_add_f32_e32 v13, v13, v33
	v_add_f32_e32 v14, v14, v34
	v_add_f32_e32 v15, v15, v35
	v_mul_f32_e32 v28, 0xbfb8aa3b, v28
	v_mul_f32_e32 v29, 0xbfb8aa3b, v29
	v_mul_f32_e32 v30, 0xbfb8aa3b, v30
	v_mul_f32_e32 v31, 0xbfb8aa3b, v31
	v_add_f32_e32 v24, v24, v32
	v_add_f32_e32 v25, v25, v33
	v_add_f32_e32 v26, v26, v34
	v_add_f32_e32 v27, v27, v35
	v_mul_f32_e32 v12, 0xbfb8aa3b, v12
	v_mul_f32_e32 v13, 0xbfb8aa3b, v13
	v_mul_f32_e32 v14, 0xbfb8aa3b, v14
	v_mul_f32_e32 v15, 0xbfb8aa3b, v15
	v_exp_f32_e32 v28, v28
	v_exp_f32_e32 v29, v29
	v_exp_f32_e32 v30, v30
	v_exp_f32_e32 v31, v31
	v_mul_f32_e32 v24, 0xbfb8aa3b, v24
	v_mul_f32_e32 v25, 0xbfb8aa3b, v25
	v_mul_f32_e32 v26, 0xbfb8aa3b, v26
	v_mul_f32_e32 v27, 0xbfb8aa3b, v27
	v_add_f32_e32 v20, v20, v32
	v_add_f32_e32 v21, v21, v33
	v_add_f32_e32 v22, v22, v34
	v_add_f32_e32 v23, v23, v35
	v_exp_f32_e32 v12, v12
	v_exp_f32_e32 v13, v13
	v_exp_f32_e32 v14, v14
	v_exp_f32_e32 v15, v15
	v_exp_f32_e32 v24, v24
	v_exp_f32_e32 v25, v25
	v_exp_f32_e32 v26, v26
	v_exp_f32_e32 v27, v27
	v_mul_f32_e32 v20, 0xbfb8aa3b, v20
	v_mul_f32_e32 v21, 0xbfb8aa3b, v21
	v_mul_f32_e32 v22, 0xbfb8aa3b, v22
	v_mul_f32_e32 v23, 0xbfb8aa3b, v23
	v_exp_f32_e32 v20, v20
	v_exp_f32_e32 v21, v21
	v_exp_f32_e32 v22, v22
	v_exp_f32_e32 v23, v23
	v_add_f32_e32 v28, 1.0, v28
	v_add_f32_e32 v29, 1.0, v29
	v_add_f32_e32 v30, 1.0, v30
	v_add_f32_e32 v31, 1.0, v31
	v_add_f32_e32 v12, 1.0, v12
	v_add_f32_e32 v13, 1.0, v13
	v_add_f32_e32 v14, 1.0, v14
	v_add_f32_e32 v15, 1.0, v15
	v_rcp_f32_e32 v28, v28
	v_rcp_f32_e32 v29, v29
	v_rcp_f32_e32 v30, v30
	v_rcp_f32_e32 v31, v31
	v_add_f32_e32 v24, 1.0, v24
	v_add_f32_e32 v25, 1.0, v25
	v_add_f32_e32 v26, 1.0, v26
	v_add_f32_e32 v27, 1.0, v27
	v_rcp_f32_e32 v12, v12
	v_rcp_f32_e32 v13, v13
	v_rcp_f32_e32 v14, v14
	v_rcp_f32_e32 v15, v15
	v_rcp_f32_e32 v24, v24
	v_rcp_f32_e32 v25, v25
	v_rcp_f32_e32 v26, v26
	v_rcp_f32_e32 v27, v27
	v_add_f32_e32 v20, 1.0, v20
	v_add_f32_e32 v21, 1.0, v21
	v_add_f32_e32 v22, 1.0, v22
	v_add_f32_e32 v23, 1.0, v23
	v_rcp_f32_e32 v20, v20
	v_rcp_f32_e32 v21, v21
	v_rcp_f32_e32 v22, v22
	v_rcp_f32_e32 v23, v23
	v_mul_f32_e32 v28, 0xbf60028b, v28
	v_mul_f32_e32 v29, 0xbf60028b, v29
	v_mul_f32_e32 v30, 0xbf60028b, v30
	v_mul_f32_e32 v31, 0xbf60028b, v31
	v_mul_f32_e32 v12, 0xbf60028b, v12
	v_mul_f32_e32 v13, 0xbf60028b, v13
	v_mul_f32_e32 v14, 0xbf60028b, v14
	v_mul_f32_e32 v15, 0xbf60028b, v15
	v_exp_f32_e32 v28, v28
	v_exp_f32_e32 v29, v29
	v_exp_f32_e32 v30, v30
	v_exp_f32_e32 v31, v31
	v_mul_f32_e32 v24, 0xbf60028b, v24
	v_mul_f32_e32 v25, 0xbf60028b, v25
	v_mul_f32_e32 v26, 0xbf60028b, v26
	v_mul_f32_e32 v27, 0xbf60028b, v27
	v_exp_f32_e32 v12, v12
	v_exp_f32_e32 v13, v13
	v_exp_f32_e32 v14, v14
	v_exp_f32_e32 v15, v15
	v_exp_f32_e32 v24, v24
	v_exp_f32_e32 v25, v25
	v_exp_f32_e32 v26, v26
	v_exp_f32_e32 v27, v27
	v_mul_f32_e32 v20, 0xbf60028b, v20
	v_mul_f32_e32 v21, 0xbf60028b, v21
	v_mul_f32_e32 v22, 0xbf60028b, v22
	v_mul_f32_e32 v23, 0xbf60028b, v23
	v_exp_f32_e32 v20, v20
	v_exp_f32_e32 v21, v21
	v_exp_f32_e32 v22, v22
	v_exp_f32_e32 v23, v23
;     __device__ __forceinline__ void operator()(const f32x4 (&acc)[2][2][4][2], const Unit& u, int wr, int wc, int fr, int fq) const {
;     ...
;         for (int bj = 0; bj < 2; ++bj)
; #pragma unroll
;             for (int n = 0; n < 2; ++n) { const f32x4 bv = *(const f32x4*)(bias + col0 + bj * HALF + n * 16);
; #pragma unroll
;                 for (int ai = 0; ai < 2; ++ai)
; #pragma unroll
;                     for (int m = 0; m < 4; ++m) { f32x4 v = acc[ai][bj][m][n] + bv, o;
; #pragma unroll
;                         for (int e = 0; e < 4; ++e) { const float z = v[e];
;                             const float sg = __builtin_amdgcn_rcpf(1.0f + __builtin_amdgcn_exp2f(-1.4426950408889634f * z));
;                             if (MODE == 0) o[e] = __builtin_amdgcn_exp2f(-0.8750387749f * sg);
;                             else o[e] = sg; }
;                         __builtin_nontemporal_store(o, (f32x4*)(O + (size_t)(row0 + ai * HALF + m * 16) * 1536 + col0 + bj * HALF + n * 16)); } }
	flat_store_dwordx4 v[136:137], v[28:31] offset:576
	flat_store_dwordx4 v[138:139], v[24:27] offset:576
	flat_store_dwordx4 v[120:121], v[20:23] offset:576
	v_add_f32_e32 v16, v16, v32
	v_add_f32_e32 v17, v17, v33
	flat_store_dwordx4 v[114:115], v[12:15] offset:576
	v_mul_f32_e32 v16, 0xbfb8aa3b, v16
	v_mul_f32_e32 v17, 0xbfb8aa3b, v17
	v_add_f32_e32 v14, v18, v34
	v_add_f32_e32 v15, v19, v35
	v_mul_f32_e32 v14, 0xbfb8aa3b, v14
	v_mul_f32_e32 v15, 0xbfb8aa3b, v15
	v_add_f32_e32 v8, v8, v32
	v_add_f32_e32 v9, v9, v33
	v_add_f32_e32 v10, v10, v34
	v_add_f32_e32 v11, v11, v35
	v_exp_f32_e32 v16, v16
	v_exp_f32_e32 v17, v17
	v_exp_f32_e32 v14, v14
	v_exp_f32_e32 v15, v15
	v_mul_f32_e32 v8, 0xbfb8aa3b, v8
	v_mul_f32_e32 v9, 0xbfb8aa3b, v9
	v_mul_f32_e32 v10, 0xbfb8aa3b, v10
	v_mul_f32_e32 v11, 0xbfb8aa3b, v11
	v_add_f32_e32 v4, v4, v32
	v_add_f32_e32 v5, v5, v33
	v_add_f32_e32 v6, v6, v34
	v_add_f32_e32 v7, v7, v35
	v_exp_f32_e32 v8, v8
	v_exp_f32_e32 v9, v9
	v_exp_f32_e32 v10, v10
	v_exp_f32_e32 v11, v11
	v_mul_f32_e32 v4, 0xbfb8aa3b, v4
	v_mul_f32_e32 v5, 0xbfb8aa3b, v5
	v_mul_f32_e32 v6, 0xbfb8aa3b, v6
	v_mul_f32_e32 v7, 0xbfb8aa3b, v7
	v_add_f32_e32 v0, v0, v32
	v_add_f32_e32 v1, v1, v33
	v_add_f32_e32 v2, v2, v34
	v_add_f32_e32 v3, v3, v35
	v_exp_f32_e32 v4, v4
	v_exp_f32_e32 v5, v5
	v_exp_f32_e32 v6, v6
	v_exp_f32_e32 v7, v7
	v_mul_f32_e32 v0, 0xbfb8aa3b, v0
	v_mul_f32_e32 v1, 0xbfb8aa3b, v1
	v_mul_f32_e32 v2, 0xbfb8aa3b, v2
	v_mul_f32_e32 v3, 0xbfb8aa3b, v3
	v_exp_f32_e32 v0, v0
	v_exp_f32_e32 v1, v1
	v_exp_f32_e32 v2, v2
	v_exp_f32_e32 v3, v3
	v_add_f32_e32 v16, 1.0, v16
	v_add_f32_e32 v13, 1.0, v17
	v_add_f32_e32 v14, 1.0, v14
	v_add_f32_e32 v15, 1.0, v15
	v_rcp_f32_e32 v16, v16
	v_rcp_f32_e32 v13, v13
	v_rcp_f32_e32 v14, v14
	v_rcp_f32_e32 v15, v15
	v_add_f32_e32 v8, 1.0, v8
	v_add_f32_e32 v9, 1.0, v9
	v_add_f32_e32 v10, 1.0, v10
	v_add_f32_e32 v11, 1.0, v11
	v_rcp_f32_e32 v8, v8
	v_rcp_f32_e32 v9, v9
	v_rcp_f32_e32 v10, v10
	v_rcp_f32_e32 v11, v11
	v_add_f32_e32 v4, 1.0, v4
	v_add_f32_e32 v5, 1.0, v5
	v_add_f32_e32 v6, 1.0, v6
	v_add_f32_e32 v7, 1.0, v7
	v_rcp_f32_e32 v4, v4
	v_rcp_f32_e32 v5, v5
	v_rcp_f32_e32 v6, v6
	v_rcp_f32_e32 v7, v7
	v_add_f32_e32 v0, 1.0, v0
	v_add_f32_e32 v1, 1.0, v1
	v_add_f32_e32 v2, 1.0, v2
	v_add_f32_e32 v3, 1.0, v3
	v_rcp_f32_e32 v0, v0
	v_rcp_f32_e32 v1, v1
	v_rcp_f32_e32 v2, v2
	v_rcp_f32_e32 v3, v3
	v_mul_f32_e32 v12, 0xbf60028b, v16
	v_mul_f32_e32 v13, 0xbf60028b, v13
	v_mul_f32_e32 v14, 0xbf60028b, v14
	v_mul_f32_e32 v15, 0xbf60028b, v15
	v_exp_f32_e32 v12, v12
	v_exp_f32_e32 v13, v13
	v_exp_f32_e32 v14, v14
	v_exp_f32_e32 v15, v15
	v_mul_f32_e32 v8, 0xbf60028b, v8
	v_mul_f32_e32 v9, 0xbf60028b, v9
	v_mul_f32_e32 v10, 0xbf60028b, v10
	v_mul_f32_e32 v11, 0xbf60028b, v11
	v_exp_f32_e32 v8, v8
	v_exp_f32_e32 v9, v9
	v_exp_f32_e32 v10, v10
	v_exp_f32_e32 v11, v11
	v_mul_f32_e32 v4, 0xbf60028b, v4
	v_mul_f32_e32 v5, 0xbf60028b, v5
	v_mul_f32_e32 v6, 0xbf60028b, v6
	v_mul_f32_e32 v7, 0xbf60028b, v7
	v_exp_f32_e32 v4, v4
	v_exp_f32_e32 v5, v5
	v_exp_f32_e32 v6, v6
	v_exp_f32_e32 v7, v7
	v_mul_f32_e32 v0, 0xbf60028b, v0
	v_mul_f32_e32 v1, 0xbf60028b, v1
	v_mul_f32_e32 v2, 0xbf60028b, v2
	v_mul_f32_e32 v3, 0xbf60028b, v3
	v_exp_f32_e32 v0, v0
	v_exp_f32_e32 v1, v1
	v_exp_f32_e32 v2, v2
	v_exp_f32_e32 v3, v3
	flat_store_dwordx4 v[112:113], v[12:15] offset:576
	flat_store_dwordx4 v[108:109], v[8:11] offset:576
	flat_store_dwordx4 v[104:105], v[4:7] offset:576
	flat_store_dwordx4 v[100:101], v[0:3] offset:576
	s_cbranch_vccnz .LBB0_373
	s_andn2_b64 vcc, exec, s[10:11]
	s_cbranch_vccnz .LBB0_372
	s_barrier
	s_branch .LBB0_372

; __global__ void __launch_bounds__(NWAVES * 64, 2) hybrid_fwd(Args A) {
;     ...
;             for (int u = bx; u < 192; u += G) { const int pm = u / 6, pn = u % 6;
;                 for (int i = 0; i < 4; i += 2) { const size_t base = (size_t)(pm * 256 + (t2 >> 6) * 32) * RW + pn * 256 + (t2 & 63) + 64 * i;
;                     float wv[32], wu[32];
; #pragma unroll
;                     for (int t = 0; t < 32; ++t) { wv[t] = __hip_atomic_load(DEC + base + (size_t)t * RW, __ATOMIC_RELAXED, __HIP_MEMORY_SCOPE_AGENT); wu[t] = __hip_atomic_load(DEC + base + 64 + (size_t)t * RW, __ATOMIC_RELAXED, __HIP_MEMORY_SCOPE_AGENT); }
;                     float gq = 1.f, gu = 1.f;
; #pragma unroll
;                     for (int t = 0; t < 32; ++t) { __builtin_nontemporal_store(gq, &GAME[base + (size_t)t * RW]); gq *= wv[t]; __builtin_nontemporal_store(gu, &GAME[base + 64 + (size_t)t * RW]); gu *= wu[t]; } } }
.LBB0_385:
	v_or_b32_e32 v5, s13, v3
	v_or_b32_e32 v4, s12, v2
	v_lshlrev_b64 v[4:5], 2, v[4:5]
	v_lshl_add_u64 v[8:9], s[8:9], 0, v[4:5]
	v_add_co_u32_e32 v10, vcc, 0x1000, v8
	v_cndmask_b32_e64 v7, 0, 1, s[14:15]
	s_nop 0
	v_addc_co_u32_e32 v11, vcc, 0, v9, vcc
	v_add_co_u32_e32 v12, vcc, 0x3000, v8
	v_cmp_ne_u32_e64 s[2:3], 1, v7
	s_nop 0
	v_addc_co_u32_e32 v13, vcc, 0, v9, vcc
	flat_load_dword v7, v[8:9] sc1
	flat_load_dword v68, v[8:9] offset:256 sc1
	flat_load_dword v69, v[10:11] offset:2048 sc1
	flat_load_dword v70, v[10:11] offset:2304 sc1
	v_add_co_u32_e32 v10, vcc, 0x4000, v8
	flat_load_dword v71, v[12:13] sc1
	flat_load_dword v72, v[12:13] offset:256 sc1
	v_addc_co_u32_e32 v11, vcc, 0, v9, vcc
	v_add_co_u32_e32 v12, vcc, 0x6000, v8
	flat_load_dword v73, v[10:11] offset:2048 sc1
	flat_load_dword v74, v[10:11] offset:2304 sc1
	v_addc_co_u32_e32 v13, vcc, 0, v9, vcc
	v_add_co_u32_e32 v10, vcc, 0x7000, v8
	flat_load_dword v75, v[12:13] sc1
	flat_load_dword v76, v[12:13] offset:256 sc1
	v_addc_co_u32_e32 v11, vcc, 0, v9, vcc
	v_add_co_u32_e32 v12, vcc, 0x9000, v8
	flat_load_dword v77, v[10:11] offset:2048 sc1
	flat_load_dword v78, v[10:11] offset:2304 sc1
	v_addc_co_u32_e32 v13, vcc, 0, v9, vcc
	v_add_co_u32_e32 v10, vcc, 0xa000, v8
	flat_load_dword v79, v[12:13] sc1
	flat_load_dword v80, v[12:13] offset:256 sc1
	v_addc_co_u32_e32 v11, vcc, 0, v9, vcc
	v_add_co_u32_e32 v12, vcc, 0xc000, v8
	flat_load_dword v81, v[10:11] offset:2048 sc1
	flat_load_dword v82, v[10:11] offset:2304 sc1
	v_addc_co_u32_e32 v13, vcc, 0, v9, vcc
	v_add_co_u32_e32 v10, vcc, 0xd000, v8
	flat_load_dword v83, v[12:13] sc1
	flat_load_dword v84, v[12:13] offset:256 sc1
	v_addc_co_u32_e32 v11, vcc, 0, v9, vcc
	v_add_co_u32_e32 v12, vcc, 0xf000, v8
	flat_load_dword v85, v[10:11] offset:2048 sc1
	flat_load_dword v86, v[10:11] offset:2304 sc1
	v_addc_co_u32_e32 v13, vcc, 0, v9, vcc
	v_add_co_u32_e32 v10, vcc, 0x10000, v8
	flat_load_dword v87, v[12:13] sc1
	flat_load_dword v88, v[12:13] offset:256 sc1
	v_addc_co_u32_e32 v11, vcc, 0, v9, vcc
	v_add_co_u32_e32 v12, vcc, 0x12000, v8
	flat_load_dword v89, v[10:11] offset:2048 sc1
	flat_load_dword v90, v[10:11] offset:2304 sc1
	v_addc_co_u32_e32 v13, vcc, 0, v9, vcc
	v_add_co_u32_e32 v10, vcc, 0x13000, v8
	flat_load_dword v91, v[12:13] sc1
	flat_load_dword v92, v[12:13] offset:256 sc1
	v_addc_co_u32_e32 v11, vcc, 0, v9, vcc
	v_add_co_u32_e32 v12, vcc, 0x15000, v8
	flat_load_dword v93, v[10:11] offset:2048 sc1
	flat_load_dword v94, v[10:11] offset:2304 sc1
	v_addc_co_u32_e32 v13, vcc, 0, v9, vcc
	v_add_co_u32_e32 v10, vcc, 0x16000, v8
	flat_load_dword v95, v[12:13] sc1
	flat_load_dword v96, v[12:13] offset:256 sc1
	v_addc_co_u32_e32 v11, vcc, 0, v9, vcc
	v_add_co_u32_e32 v12, vcc, 0x18000, v8
	flat_load_dword v97, v[10:11] offset:2048 sc1
	flat_load_dword v98, v[10:11] offset:2304 sc1
	v_addc_co_u32_e32 v13, vcc, 0, v9, vcc
	v_add_co_u32_e32 v10, vcc, 0x19000, v8
	flat_load_dword v99, v[12:13] sc1
	flat_load_dword v100, v[12:13] offset:256 sc1
	v_addc_co_u32_e32 v11, vcc, 0, v9, vcc
	v_add_co_u32_e32 v12, vcc, 0x1b000, v8
	flat_load_dword v101, v[10:11] offset:2048 sc1
	flat_load_dword v102, v[10:11] offset:2304 sc1
	v_addc_co_u32_e32 v13, vcc, 0, v9, vcc
	v_add_co_u32_e32 v10, vcc, 0x1c000, v8
	flat_load_dword v103, v[12:13] sc1
	flat_load_dword v104, v[12:13] offset:256 sc1
	v_addc_co_u32_e32 v11, vcc, 0, v9, vcc
	v_add_co_u32_e32 v12, vcc, 0x1e000, v8
	flat_load_dword v105, v[10:11] offset:2048 sc1
	flat_load_dword v106, v[10:11] offset:2304 sc1
	v_addc_co_u32_e32 v13, vcc, 0, v9, vcc
	v_add_co_u32_e32 v10, vcc, 0x1f000, v8
	flat_load_dword v107, v[12:13] sc1
	flat_load_dword v108, v[12:13] offset:256 sc1
	v_addc_co_u32_e32 v11, vcc, 0, v9, vcc
	v_add_co_u32_e32 v12, vcc, 0x21000, v8
	flat_load_dword v109, v[10:11] offset:2048 sc1
	flat_load_dword v110, v[10:11] offset:2304 sc1
	v_addc_co_u32_e32 v13, vcc, 0, v9, vcc
	v_add_co_u32_e32 v10, vcc, 0x22000, v8
	flat_load_dword v111, v[12:13] sc1
	flat_load_dword v112, v[12:13] offset:256 sc1
	v_addc_co_u32_e32 v11, vcc, 0, v9, vcc
	v_add_co_u32_e32 v12, vcc, 0x24000, v8
	flat_load_dword v113, v[10:11] offset:2048 sc1
	flat_load_dword v114, v[10:11] offset:2304 sc1
	v_addc_co_u32_e32 v13, vcc, 0, v9, vcc
	v_add_co_u32_e32 v10, vcc, 0x25000, v8
	flat_load_dword v115, v[12:13] sc1
	flat_load_dword v116, v[12:13] offset:256 sc1
	v_addc_co_u32_e32 v11, vcc, 0, v9, vcc
	v_add_co_u32_e32 v12, vcc, 0x27000, v8
	flat_load_dword v117, v[10:11] offset:2048 sc1
	flat_load_dword v118, v[10:11] offset:2304 sc1
	v_addc_co_u32_e32 v13, vcc, 0, v9, vcc
	v_add_co_u32_e32 v10, vcc, 0x28000, v8
	flat_load_dword v119, v[12:13] sc1
	flat_load_dword v120, v[12:13] offset:256 sc1
	v_addc_co_u32_e32 v11, vcc, 0, v9, vcc
	v_add_co_u32_e32 v12, vcc, 0x2a000, v8
	flat_load_dword v121, v[10:11] offset:2048 sc1
	flat_load_dword v122, v[10:11] offset:2304 sc1
	v_addc_co_u32_e32 v13, vcc, 0, v9, vcc
	v_add_co_u32_e32 v10, vcc, 0x2b000, v8
	flat_load_dword v123, v[12:13] sc1
	flat_load_dword v124, v[12:13] offset:256 sc1
	v_addc_co_u32_e32 v11, vcc, 0, v9, vcc
	v_add_co_u32_e32 v12, vcc, 0x2d000, v8
	flat_load_dword v125, v[10:11] offset:2048 sc1
	flat_load_dword v126, v[10:11] offset:2304 sc1
	v_addc_co_u32_e32 v13, vcc, 0, v9, vcc
	v_add_co_u32_e32 v8, vcc, 0x2e000, v8
	flat_load_dword v127, v[12:13] sc1
	flat_load_dword v128, v[12:13] offset:256 sc1
	v_addc_co_u32_e32 v9, vcc, 0, v9, vcc
	flat_load_dword v11, v[8:9] offset:2048 sc1
	s_nop 0
	flat_load_dword v8, v[8:9] offset:2304 sc1
	v_lshl_add_u64 v[4:5], s[10:11], 0, v[4:5]
	v_add_co_u32_e32 v10, vcc, s1, v4
	flat_store_dword v[4:5], v6
	flat_store_dword v[4:5], v6 offset:256
	s_waitcnt vmcnt(0) lgkmcnt(0)
; __global__ void __launch_bounds__(NWAVES * 64, 2) hybrid_fwd(Args A) {
;     ...
;                     for (int t = 0; t < 32; ++t) { wv[t] = __hip_atomic_load(DEC + base + (size_t)t * RW, __ATOMIC_RELAXED, __HIP_MEMORY_SCOPE_AGENT); wu[t] = __hip_atomic_load(DEC + base + 64 + (size_t)t * RW, __ATOMIC_RELAXED, __HIP_MEMORY_SCOPE_AGENT); }
;                     float gq = 1.f, gu = 1.f;
; #pragma unroll
;                     for (int t = 0; t < 32; ++t) { __builtin_nontemporal_store(gq, &GAME[base + (size_t)t * RW]); gq *= wv[t]; __builtin_nontemporal_store(gu, &GAME[base + 64 + (size_t)t * RW]); gu *= wu[t]; } } }
	v_addc_co_u32_e32 v11, vcc, 0, v5, vcc
	v_add_co_u32_e32 v8, vcc, s16, v4
	flat_store_dword v[10:11], v7 offset:2048
	flat_store_dword v[10:11], v68 offset:2304
	v_addc_co_u32_e32 v9, vcc, 0, v5, vcc
	v_add_co_u32_e32 v12, vcc, s17, v4
	v_mul_f32_e32 v7, v7, v69
	s_nop 0
	v_addc_co_u32_e32 v13, vcc, 0, v5, vcc
	v_add_co_u32_e32 v14, vcc, s18, v4
	v_mul_f32_e32 v10, v68, v70
	s_nop 0
	v_addc_co_u32_e32 v15, vcc, 0, v5, vcc
	v_add_co_u32_e32 v16, vcc, s19, v4
	flat_store_dword v[8:9], v7
	s_nop 0
	v_addc_co_u32_e32 v17, vcc, 0, v5, vcc
	v_add_co_u32_e32 v18, vcc, s20, v4
	v_mul_f32_e32 v7, v7, v71
	s_nop 0
	v_addc_co_u32_e32 v19, vcc, 0, v5, vcc
	v_add_co_u32_e32 v20, vcc, s21, v4
	flat_store_dword v[8:9], v10 offset:256
	s_nop 0
	v_addc_co_u32_e32 v21, vcc, 0, v5, vcc
	v_add_co_u32_e32 v22, vcc, s22, v4
	v_mul_f32_e32 v8, v10, v72
	s_nop 0
	v_addc_co_u32_e32 v23, vcc, 0, v5, vcc
	v_add_co_u32_e32 v24, vcc, s23, v4
	flat_store_dword v[12:13], v7 offset:2048
	s_nop 0
	v_addc_co_u32_e32 v25, vcc, 0, v5, vcc
	v_add_co_u32_e32 v26, vcc, s24, v4
	v_mul_f32_e32 v7, v7, v73
	s_nop 0
	v_addc_co_u32_e32 v27, vcc, 0, v5, vcc
	v_add_co_u32_e32 v28, vcc, s25, v4
	flat_store_dword v[12:13], v8 offset:2304
	s_nop 0
	v_addc_co_u32_e32 v29, vcc, 0, v5, vcc
	v_add_co_u32_e32 v30, vcc, s26, v4
	v_mul_f32_e32 v8, v8, v74
	s_nop 0
	v_addc_co_u32_e32 v31, vcc, 0, v5, vcc
	v_add_co_u32_e32 v32, vcc, s27, v4
	flat_store_dword v[14:15], v7
	s_nop 0
	v_addc_co_u32_e32 v33, vcc, 0, v5, vcc
	v_add_co_u32_e32 v34, vcc, s28, v4
	v_mul_f32_e32 v7, v7, v75
	s_nop 0
	v_addc_co_u32_e32 v35, vcc, 0, v5, vcc
	v_add_co_u32_e32 v36, vcc, s29, v4
	flat_store_dword v[14:15], v8 offset:256
	s_nop 0
	v_addc_co_u32_e32 v37, vcc, 0, v5, vcc
	v_add_co_u32_e32 v38, vcc, s30, v4
	v_mul_f32_e32 v8, v8, v76
	s_nop 0
	v_addc_co_u32_e32 v39, vcc, 0, v5, vcc
	v_add_co_u32_e32 v40, vcc, s33, v4
	flat_store_dword v[16:17], v7 offset:2048
	s_nop 0
	v_addc_co_u32_e32 v41, vcc, 0, v5, vcc
	v_add_co_u32_e32 v42, vcc, s38, v4
	v_mul_f32_e32 v7, v7, v77
	s_nop 0
	v_addc_co_u32_e32 v43, vcc, 0, v5, vcc
	v_add_co_u32_e32 v44, vcc, s39, v4
	flat_store_dword v[16:17], v8 offset:2304
	s_nop 0
	v_addc_co_u32_e32 v45, vcc, 0, v5, vcc
	v_add_co_u32_e32 v46, vcc, s40, v4
	v_mul_f32_e32 v8, v8, v78
	flat_store_dword v[18:19], v7
	v_mul_f32_e32 v7, v7, v79
	v_addc_co_u32_e32 v47, vcc, 0, v5, vcc
	flat_store_dword v[18:19], v8 offset:256
	v_mul_f32_e32 v8, v8, v80
	flat_store_dword v[20:21], v7 offset:2048
	v_mul_f32_e32 v7, v7, v81
	v_add_co_u32_e32 v48, vcc, s41, v4
	flat_store_dword v[20:21], v8 offset:2304
	v_mul_f32_e32 v8, v8, v82
	flat_store_dword v[22:23], v7
	v_mul_f32_e32 v7, v7, v83
	v_addc_co_u32_e32 v49, vcc, 0, v5, vcc
	flat_store_dword v[22:23], v8 offset:256
	v_mul_f32_e32 v8, v8, v84
	flat_store_dword v[24:25], v7 offset:2048
	v_mul_f32_e32 v7, v7, v85
	v_add_co_u32_e32 v50, vcc, s42, v4
	flat_store_dword v[24:25], v8 offset:2304
	v_mul_f32_e32 v8, v8, v86
	flat_store_dword v[26:27], v7
	v_mul_f32_e32 v7, v7, v87
	v_addc_co_u32_e32 v51, vcc, 0, v5, vcc
	flat_store_dword v[26:27], v8 offset:256
	v_mul_f32_e32 v8, v8, v88
	flat_store_dword v[28:29], v7 offset:2048
	v_mul_f32_e32 v7, v7, v89
	v_add_co_u32_e32 v52, vcc, s43, v4
	flat_store_dword v[28:29], v8 offset:2304
	v_mul_f32_e32 v8, v8, v90
	flat_store_dword v[30:31], v7
	v_mul_f32_e32 v7, v7, v91
	v_addc_co_u32_e32 v53, vcc, 0, v5, vcc
	flat_store_dword v[30:31], v8 offset:256
	v_mul_f32_e32 v8, v8, v92
	flat_store_dword v[32:33], v7 offset:2048
	v_mul_f32_e32 v7, v7, v93
	v_add_co_u32_e32 v54, vcc, s46, v4
	flat_store_dword v[32:33], v8 offset:2304
	v_mul_f32_e32 v8, v8, v94
	flat_store_dword v[34:35], v7
	v_mul_f32_e32 v7, v7, v95
	v_addc_co_u32_e32 v55, vcc, 0, v5, vcc
	flat_store_dword v[34:35], v8 offset:256
	v_mul_f32_e32 v8, v8, v96
	flat_store_dword v[36:37], v7 offset:2048
	v_mul_f32_e32 v7, v7, v97
	v_add_co_u32_e32 v56, vcc, s47, v4
	flat_store_dword v[36:37], v8 offset:2304
	v_mul_f32_e32 v8, v8, v98
	flat_store_dword v[38:39], v7
	v_mul_f32_e32 v7, v7, v99
	v_addc_co_u32_e32 v57, vcc, 0, v5, vcc
	flat_store_dword v[38:39], v8 offset:256
	v_mul_f32_e32 v8, v8, v100
	flat_store_dword v[40:41], v7 offset:2048
	v_mul_f32_e32 v7, v7, v101
	v_add_co_u32_e32 v58, vcc, s48, v4
	flat_store_dword v[40:41], v8 offset:2304
	v_mul_f32_e32 v8, v8, v102
	flat_store_dword v[42:43], v7
	v_mul_f32_e32 v7, v7, v103
	v_addc_co_u32_e32 v59, vcc, 0, v5, vcc
	flat_store_dword v[42:43], v8 offset:256
	v_mul_f32_e32 v8, v8, v104
	flat_store_dword v[44:45], v7 offset:2048
	v_mul_f32_e32 v7, v7, v105
	v_add_co_u32_e32 v60, vcc, s49, v4
	flat_store_dword v[44:45], v8 offset:2304
	v_mul_f32_e32 v8, v8, v106
	flat_store_dword v[46:47], v7
	v_mul_f32_e32 v7, v7, v107
	v_addc_co_u32_e32 v61, vcc, 0, v5, vcc
	flat_store_dword v[46:47], v8 offset:256
	v_mul_f32_e32 v8, v8, v108
	flat_store_dword v[48:49], v7 offset:2048
	v_mul_f32_e32 v7, v7, v109
	v_add_co_u32_e32 v62, vcc, s53, v4
	flat_store_dword v[48:49], v8 offset:2304
	v_mul_f32_e32 v8, v8, v110
	flat_store_dword v[50:51], v7
	v_mul_f32_e32 v7, v7, v111
	v_addc_co_u32_e32 v63, vcc, 0, v5, vcc
	flat_store_dword v[50:51], v8 offset:256
	v_mul_f32_e32 v8, v8, v112
	flat_store_dword v[52:53], v7 offset:2048
	v_mul_f32_e32 v7, v7, v113
	v_add_co_u32_e32 v64, vcc, s64, v4
	flat_store_dword v[52:53], v8 offset:2304
	v_mul_f32_e32 v8, v8, v114
	flat_store_dword v[54:55], v7
	v_mul_f32_e32 v7, v7, v115
	v_addc_co_u32_e32 v65, vcc, 0, v5, vcc
	flat_store_dword v[54:55], v8 offset:256
	v_mul_f32_e32 v8, v8, v116
	flat_store_dword v[56:57], v7 offset:2048
	v_mul_f32_e32 v7, v7, v117
	v_add_co_u32_e32 v66, vcc, 0x2d000, v4
	flat_store_dword v[56:57], v8 offset:2304
	v_mul_f32_e32 v8, v8, v118
	flat_store_dword v[58:59], v7
	v_mul_f32_e32 v7, v7, v119
	v_addc_co_u32_e32 v67, vcc, 0, v5, vcc
	flat_store_dword v[58:59], v8 offset:256
	v_mul_f32_e32 v8, v8, v120
	flat_store_dword v[60:61], v7 offset:2048
	v_mul_f32_e32 v7, v7, v121
	v_add_co_u32_e32 v4, vcc, 0x2e000, v4
	flat_store_dword v[60:61], v8 offset:2304
	v_mul_f32_e32 v8, v8, v122
	flat_store_dword v[62:63], v7
	v_mul_f32_e32 v7, v7, v123
	v_addc_co_u32_e32 v5, vcc, 0, v5, vcc
	flat_store_dword v[62:63], v8 offset:256
	v_mul_f32_e32 v8, v8, v124
	flat_store_dword v[64:65], v7 offset:2048
	v_mul_f32_e32 v7, v7, v125
	s_mov_b64 s[12:13], 0x80
	s_mov_b64 s[14:15], 0
	s_and_b64 vcc, exec, s[2:3]
	flat_store_dword v[64:65], v8 offset:2304
	v_mul_f32_e32 v8, v8, v126
	flat_store_dword v[66:67], v7
	v_mul_f32_e32 v7, v7, v127
	flat_store_dword v[66:67], v8 offset:256
	v_mul_f32_e32 v8, v8, v128
	flat_store_dword v[4:5], v7 offset:2048
	flat_store_dword v[4:5], v8 offset:2304
	s_cbranch_vccz .LBB0_385
	s_add_i32 s65, s65, s31
	s_cmpk_gt_i32 s65, 0xbf
	s_cbranch_scc0 .LBB0_384

;     __device__ __forceinline__ void operator()(const f32x4 (&acc)[2][2][4][2], const Unit& u, int wr, int wc, int fr, int fq) const {
;         const int row0 = u.pm * BM + wr * 64 + fr, col0 = u.pn * BM + wc * 32 + 4 * fq;
; #pragma unroll
;         for (int bj = 0; bj < 2; ++bj)
; #pragma unroll
;             for (int n = 0; n < 2; ++n) { const f32x4 bv = *(const f32x4*)(bias + col0 + bj * HALF + n * 16);
; #pragma unroll
;                 for (int ai = 0; ai < 2; ++ai)
; #pragma unroll
;                     for (int m = 0; m < 4; ++m) { f32x4 v = acc[ai][bj][m][n] + bv, o;
; #pragma unroll
;                         for (int e = 0; e < 4; ++e) { const float z = v[e];
;                             const float sg = __builtin_amdgcn_rcpf(1.0f + __builtin_amdgcn_exp2f(-1.4426950408889634f * z));
;                             if (MODE == 0) o[e] = __builtin_amdgcn_exp2f(-0.8750387749f * sg);
;                             else o[e] = sg; }
;                         __builtin_nontemporal_store(o, (f32x4*)(O + (size_t)(row0 + ai * HALF + m * 16) * 1536 + col0 + bj * HALF + n * 16)); } }
.LBB0_397:
	s_load_dwordx16 s[80:95], s[62:63], 0x0
	v_lshl_or_b32 v104, s0, 8, v149
	v_ashrrev_i32_e32 v105, 31, v104
	v_lshlrev_b64 v[144:145], 2, v[104:105]
	v_lshl_add_u32 v155, s1, 8, v148
	s_waitcnt lgkmcnt(0)
	v_lshl_add_u64 v[138:139], s[94:95], 0, v[144:145]
	global_load_dwordx4 v[104:107], v[138:139], off
	global_load_dwordx4 v[212:215], v[138:139], off offset:64
	global_load_dwordx4 v[216:219], v[138:139], off offset:512
	global_load_dwordx4 v[220:223], v[138:139], off offset:576
	v_mov_b64_e32 v[146:147], s[6:7]
	v_or_b32_e32 v142, 32, v155
	v_mad_i64_i32 v[136:137], s[0:1], v155, s25, v[146:147]
	v_mad_i64_i32 v[156:157], s[0:1], v142, s25, v[146:147]
	v_lshl_add_u64 v[142:143], v[136:137], 0, v[144:145]
	v_lshl_add_u64 v[136:137], v[156:157], 0, v[144:145]
	v_or_b32_e32 v140, 16, v155
	v_mad_i64_i32 v[140:141], s[0:1], v140, s25, v[146:147]
	v_lshl_add_u64 v[140:141], v[140:141], 0, v[144:145]
	s_andn2_b64 vcc, exec, s[20:21]
	s_mov_b64 s[20:21], -1
	s_waitcnt vmcnt(0)
	v_add_f32_e32 v120, v120, v104
	v_add_f32_e32 v121, v121, v105
	v_add_f32_e32 v122, v122, v106
	v_add_f32_e32 v123, v123, v107
	v_add_f32_e32 v124, v124, v104
	v_add_f32_e32 v125, v125, v105
	v_add_f32_e32 v126, v126, v106
	v_add_f32_e32 v127, v127, v107
	v_add_f32_e32 v128, v128, v104
	v_add_f32_e32 v129, v129, v105
	v_add_f32_e32 v130, v130, v106
	v_add_f32_e32 v131, v131, v107
	v_add_f32_e32 v116, v116, v104
	v_add_f32_e32 v117, v117, v105
	v_mul_f32_e32 v120, 0xbfb8aa3b, v120
	v_mul_f32_e32 v121, 0xbfb8aa3b, v121
	v_mul_f32_e32 v122, 0xbfb8aa3b, v122
	v_mul_f32_e32 v123, 0xbfb8aa3b, v123
	v_mul_f32_e32 v124, 0xbfb8aa3b, v124
	v_mul_f32_e32 v125, 0xbfb8aa3b, v125
	v_mul_f32_e32 v126, 0xbfb8aa3b, v126
	v_mul_f32_e32 v127, 0xbfb8aa3b, v127
	v_mul_f32_e32 v128, 0xbfb8aa3b, v128
	v_mul_f32_e32 v129, 0xbfb8aa3b, v129
	v_mul_f32_e32 v130, 0xbfb8aa3b, v130
	v_mul_f32_e32 v131, 0xbfb8aa3b, v131
	v_mul_f32_e32 v116, 0xbfb8aa3b, v116
	v_mul_f32_e32 v117, 0xbfb8aa3b, v117
	v_exp_f32_e32 v120, v120
	v_exp_f32_e32 v121, v121
	v_exp_f32_e32 v122, v122
	v_exp_f32_e32 v123, v123
	v_exp_f32_e32 v124, v124
	v_exp_f32_e32 v125, v125
	v_exp_f32_e32 v126, v126
	v_exp_f32_e32 v127, v127
	v_exp_f32_e32 v128, v128
	v_exp_f32_e32 v129, v129
	v_exp_f32_e32 v130, v130
	v_exp_f32_e32 v131, v131
	v_exp_f32_e32 v116, v116
	v_exp_f32_e32 v117, v117
	v_add_f32_e32 v118, v118, v106
	v_add_f32_e32 v119, v119, v107
	v_add_f32_e32 v112, v112, v104
	v_mul_f32_e32 v118, 0xbfb8aa3b, v118
	v_mul_f32_e32 v119, 0xbfb8aa3b, v119
	v_mul_f32_e32 v112, 0xbfb8aa3b, v112
	v_add_f32_e32 v113, v113, v105
	v_exp_f32_e32 v156, v118
	v_exp_f32_e32 v157, v119
	v_add_f32_e32 v118, 1.0, v120
	v_add_f32_e32 v119, 1.0, v121
	v_add_f32_e32 v120, 1.0, v122
	v_add_f32_e32 v121, 1.0, v123
	v_exp_f32_e32 v112, v112
	v_mul_f32_e32 v113, 0xbfb8aa3b, v113
	v_add_f32_e32 v122, 1.0, v124
	v_add_f32_e32 v123, 1.0, v125
	v_add_f32_e32 v124, 1.0, v126
	v_add_f32_e32 v125, 1.0, v127
	v_add_f32_e32 v126, 1.0, v128
	v_add_f32_e32 v127, 1.0, v129
	v_add_f32_e32 v128, 1.0, v130
	v_add_f32_e32 v129, 1.0, v131
	v_add_f32_e32 v130, 1.0, v116
	v_add_f32_e32 v131, 1.0, v117
	v_rcp_f32_e32 v116, v118
	v_rcp_f32_e32 v117, v119
	v_rcp_f32_e32 v118, v120
	v_rcp_f32_e32 v119, v121
	v_exp_f32_e32 v113, v113
	v_rcp_f32_e32 v120, v122
	v_rcp_f32_e32 v121, v123
	v_rcp_f32_e32 v122, v124
	v_rcp_f32_e32 v123, v125
	v_rcp_f32_e32 v124, v126
	v_rcp_f32_e32 v125, v127
	v_rcp_f32_e32 v126, v128
	v_rcp_f32_e32 v127, v129
	v_add_f32_e32 v112, 1.0, v112
	flat_store_dwordx4 v[142:143], v[116:119]
	flat_store_dwordx4 v[140:141], v[120:123]
	flat_store_dwordx4 v[136:137], v[124:127]
	v_rcp_f32_e32 v118, v112
	v_add_f32_e32 v112, 1.0, v113
	v_add_f32_e32 v113, v114, v106
	v_mul_f32_e32 v113, 0xbfb8aa3b, v113
	v_add_f32_e32 v114, v115, v107
	v_exp_f32_e32 v113, v113
	v_mul_f32_e32 v114, 0xbfb8aa3b, v114
	v_exp_f32_e32 v114, v114
	v_add_f32_e32 v108, v108, v104
	v_rcp_f32_e32 v119, v112
	v_add_f32_e32 v112, 1.0, v113
	v_mul_f32_e32 v108, 0xbfb8aa3b, v108
	v_add_f32_e32 v109, v109, v105
	v_rcp_f32_e32 v120, v112
	v_add_f32_e32 v112, 1.0, v114
	v_exp_f32_e32 v108, v108
	v_mul_f32_e32 v109, 0xbfb8aa3b, v109
	v_rcp_f32_e32 v121, v112
	v_exp_f32_e32 v109, v109
	v_add_u32_e32 v122, 0x80, v155
	v_mad_i64_i32 v[112:113], s[0:1], v122, s25, v[146:147]
	v_lshl_add_u64 v[112:113], v[112:113], 0, v[144:145]
	v_add_f32_e32 v108, 1.0, v108
	flat_store_dwordx4 v[112:113], v[118:121]
	v_add_f32_e32 v100, v100, v104
	v_mul_f32_e32 v100, 0xbfb8aa3b, v100
	v_rcp_f32_e32 v118, v108
	v_add_f32_e32 v108, 1.0, v109
	v_add_f32_e32 v109, v110, v106
	v_mul_f32_e32 v109, 0xbfb8aa3b, v109
	v_add_f32_e32 v110, v111, v107
	v_exp_f32_e32 v109, v109
	v_mul_f32_e32 v110, 0xbfb8aa3b, v110
	v_exp_f32_e32 v110, v110
	v_rcp_f32_e32 v119, v108
	v_add_f32_e32 v108, 1.0, v109
	v_add_f32_e32 v101, v101, v105
	v_rcp_f32_e32 v120, v108
	v_add_f32_e32 v108, 1.0, v110
	v_exp_f32_e32 v100, v100
	v_mul_f32_e32 v101, 0xbfb8aa3b, v101
	v_rcp_f32_e32 v121, v108
	v_exp_f32_e32 v101, v101
	v_add_u32_e32 v108, 0x90, v155
	v_mad_i64_i32 v[108:109], s[0:1], v108, s25, v[146:147]
	v_lshl_add_u64 v[108:109], v[108:109], 0, v[144:145]
	v_add_f32_e32 v100, 1.0, v100
	flat_store_dwordx4 v[108:109], v[118:121]
	v_add_f32_e32 v96, v96, v104
	v_mul_f32_e32 v96, 0xbfb8aa3b, v96
	v_rcp_f32_e32 v118, v100
	v_add_f32_e32 v100, 1.0, v101
	v_add_f32_e32 v101, v102, v106
	v_mul_f32_e32 v101, 0xbfb8aa3b, v101
	v_add_f32_e32 v102, v103, v107
	v_add_f32_e32 v97, v97, v105
	v_exp_f32_e32 v101, v101
	v_mul_f32_e32 v102, 0xbfb8aa3b, v102
	v_exp_f32_e32 v96, v96
	v_mul_f32_e32 v97, 0xbfb8aa3b, v97
	v_exp_f32_e32 v102, v102
;     __device__ __forceinline__ void operator()(const f32x4 (&acc)[2][2][4][2], const Unit& u, int wr, int wc, int fr, int fq) const {
;     ...
;         for (int bj = 0; bj < 2; ++bj)
; #pragma unroll
;             for (int n = 0; n < 2; ++n) { const f32x4 bv = *(const f32x4*)(bias + col0 + bj * HALF + n * 16);
; #pragma unroll
;                 for (int ai = 0; ai < 2; ++ai)
; #pragma unroll
;                     for (int m = 0; m < 4; ++m) { f32x4 v = acc[ai][bj][m][n] + bv, o;
; #pragma unroll
;                         for (int e = 0; e < 4; ++e) { const float z = v[e];
;                             const float sg = __builtin_amdgcn_rcpf(1.0f + __builtin_amdgcn_exp2f(-1.4426950408889634f * z));
;                             if (MODE == 0) o[e] = __builtin_amdgcn_exp2f(-0.8750387749f * sg);
;                             else o[e] = sg; }
;                         __builtin_nontemporal_store(o, (f32x4*)(O + (size_t)(row0 + ai * HALF + m * 16) * 1536 + col0 + bj * HALF + n * 16)); } }
	v_exp_f32_e32 v97, v97
	v_rcp_f32_e32 v119, v100
	v_add_f32_e32 v100, 1.0, v101
	v_add_f32_e32 v96, 1.0, v96
	v_rcp_f32_e32 v120, v100
	v_add_f32_e32 v100, 1.0, v102
	v_rcp_f32_e32 v102, v96
	v_add_f32_e32 v96, 1.0, v97
	v_add_f32_e32 v97, v98, v106
	v_mul_f32_e32 v97, 0xbfb8aa3b, v97
	v_add_f32_e32 v98, v99, v107
	v_exp_f32_e32 v97, v97
	v_mul_f32_e32 v98, 0xbfb8aa3b, v98
	v_exp_f32_e32 v98, v98
	v_add_f32_e32 v116, 1.0, v156
	v_rcp_f32_e32 v103, v96
	v_add_f32_e32 v96, 1.0, v97
	v_rcp_f32_e32 v128, v130
	v_rcp_f32_e32 v130, v116
	v_add_f32_e32 v116, 1.0, v157
	v_rcp_f32_e32 v104, v96
	v_add_f32_e32 v96, 1.0, v98
	v_rcp_f32_e32 v129, v131
	v_rcp_f32_e32 v131, v116
	v_rcp_f32_e32 v121, v100
	v_rcp_f32_e32 v105, v96
	v_or_b32_e32 v116, 48, v155
	v_add_u32_e32 v100, 0xa0, v155
	v_add_u32_e32 v96, 0xb0, v155
	v_mad_i64_i32 v[116:117], s[0:1], v116, s25, v[146:147]
	v_mad_i64_i32 v[100:101], s[0:1], v100, s25, v[146:147]
	v_mad_i64_i32 v[96:97], s[0:1], v96, s25, v[146:147]
	v_lshl_add_u64 v[116:117], v[116:117], 0, v[144:145]
	v_lshl_add_u64 v[100:101], v[100:101], 0, v[144:145]
	v_lshl_add_u64 v[96:97], v[96:97], 0, v[144:145]
	flat_store_dwordx4 v[116:117], v[128:131]
	flat_store_dwordx4 v[100:101], v[118:121]
	flat_store_dwordx4 v[96:97], v[102:105]
	s_nop 3
	v_mov_b64_e32 v[102:103], v[212:213]
	v_mov_b64_e32 v[104:105], v[214:215]
	v_add_f32_e32 v80, v80, v102
	v_add_f32_e32 v81, v81, v103
	v_add_f32_e32 v82, v82, v104
	v_add_f32_e32 v83, v83, v105
	v_add_f32_e32 v72, v72, v102
	v_add_f32_e32 v73, v73, v103
	v_add_f32_e32 v74, v74, v104
	v_add_f32_e32 v75, v75, v105
	v_mul_f32_e32 v80, 0xbfb8aa3b, v80
	v_mul_f32_e32 v81, 0xbfb8aa3b, v81
	v_mul_f32_e32 v82, 0xbfb8aa3b, v82
	v_mul_f32_e32 v83, 0xbfb8aa3b, v83
	v_mul_f32_e32 v72, 0xbfb8aa3b, v72
	v_mul_f32_e32 v73, 0xbfb8aa3b, v73
	v_mul_f32_e32 v74, 0xbfb8aa3b, v74
	v_mul_f32_e32 v75, 0xbfb8aa3b, v75
	v_exp_f32_e32 v80, v80
	v_exp_f32_e32 v81, v81
	v_exp_f32_e32 v82, v82
	v_exp_f32_e32 v83, v83
	v_exp_f32_e32 v72, v72
	v_exp_f32_e32 v73, v73
	v_exp_f32_e32 v74, v74
	v_exp_f32_e32 v75, v75
	v_add_f32_e32 v80, 1.0, v80
	v_add_f32_e32 v81, 1.0, v81
	v_add_f32_e32 v82, 1.0, v82
	v_add_f32_e32 v83, 1.0, v83
	v_add_f32_e32 v72, 1.0, v72
	v_add_f32_e32 v73, 1.0, v73
	v_add_f32_e32 v74, 1.0, v74
	v_add_f32_e32 v75, 1.0, v75
	v_rcp_f32_e32 v80, v80
	v_rcp_f32_e32 v81, v81
	v_rcp_f32_e32 v82, v82
	v_rcp_f32_e32 v83, v83
	v_rcp_f32_e32 v72, v72
	v_rcp_f32_e32 v73, v73
	v_rcp_f32_e32 v74, v74
	v_rcp_f32_e32 v75, v75
	v_add_f32_e32 v92, v92, v102
	v_add_f32_e32 v93, v93, v103
	v_add_f32_e32 v94, v94, v104
	v_add_f32_e32 v95, v95, v105
	v_add_f32_e32 v88, v88, v102
	v_add_f32_e32 v89, v89, v103
	v_add_f32_e32 v90, v90, v104
	v_add_f32_e32 v91, v91, v105
	flat_store_dwordx4 v[136:137], v[80:83] offset:64
	flat_store_dwordx4 v[116:117], v[72:75] offset:64
	v_mul_f32_e32 v92, 0xbfb8aa3b, v92
	v_add_f32_e32 v80, v84, v102
	v_add_f32_e32 v81, v85, v103
	v_add_f32_e32 v74, v86, v104
	v_add_f32_e32 v75, v87, v105
	v_mul_f32_e32 v93, 0xbfb8aa3b, v93
	v_mul_f32_e32 v94, 0xbfb8aa3b, v94
	v_mul_f32_e32 v95, 0xbfb8aa3b, v95
	v_mul_f32_e32 v88, 0xbfb8aa3b, v88
	v_mul_f32_e32 v89, 0xbfb8aa3b, v89
	v_mul_f32_e32 v90, 0xbfb8aa3b, v90
	v_mul_f32_e32 v91, 0xbfb8aa3b, v91
	v_mul_f32_e32 v80, 0xbfb8aa3b, v80
	v_mul_f32_e32 v81, 0xbfb8aa3b, v81
	v_mul_f32_e32 v74, 0xbfb8aa3b, v74
	v_mul_f32_e32 v75, 0xbfb8aa3b, v75
	v_add_f32_e32 v76, v76, v102
	v_add_f32_e32 v77, v77, v103
	v_add_f32_e32 v78, v78, v104
	v_add_f32_e32 v79, v79, v105
	v_exp_f32_e32 v92, v92
	v_exp_f32_e32 v93, v93
	v_exp_f32_e32 v94, v94
	v_exp_f32_e32 v95, v95
	v_exp_f32_e32 v88, v88
	v_exp_f32_e32 v89, v89
	v_exp_f32_e32 v90, v90
	v_exp_f32_e32 v91, v91
	v_exp_f32_e32 v80, v80
	v_exp_f32_e32 v81, v81
	v_exp_f32_e32 v74, v74
	v_exp_f32_e32 v75, v75
	v_mul_f32_e32 v76, 0xbfb8aa3b, v76
	v_mul_f32_e32 v77, 0xbfb8aa3b, v77
	v_mul_f32_e32 v78, 0xbfb8aa3b, v78
	v_mul_f32_e32 v79, 0xbfb8aa3b, v79
	v_add_f32_e32 v68, v68, v102
	v_add_f32_e32 v69, v69, v103
	v_add_f32_e32 v70, v70, v104
	v_add_f32_e32 v71, v71, v105
	v_exp_f32_e32 v76, v76
	v_exp_f32_e32 v77, v77
	v_exp_f32_e32 v78, v78
	v_exp_f32_e32 v79, v79
	v_mul_f32_e32 v68, 0xbfb8aa3b, v68
	v_mul_f32_e32 v69, 0xbfb8aa3b, v69
	v_mul_f32_e32 v70, 0xbfb8aa3b, v70
	v_mul_f32_e32 v71, 0xbfb8aa3b, v71
	v_add_f32_e32 v64, v64, v102
	v_add_f32_e32 v65, v65, v103
	v_add_f32_e32 v66, v66, v104
	v_add_f32_e32 v67, v67, v105
	v_exp_f32_e32 v68, v68
	v_exp_f32_e32 v69, v69
	v_exp_f32_e32 v70, v70
	v_exp_f32_e32 v71, v71
	v_mul_f32_e32 v64, 0xbfb8aa3b, v64
	v_mul_f32_e32 v65, 0xbfb8aa3b, v65
	v_mul_f32_e32 v66, 0xbfb8aa3b, v66
	v_mul_f32_e32 v67, 0xbfb8aa3b, v67
	v_exp_f32_e32 v64, v64
	v_exp_f32_e32 v65, v65
	v_exp_f32_e32 v66, v66
	v_exp_f32_e32 v67, v67
	v_add_f32_e32 v92, 1.0, v92
	v_add_f32_e32 v93, 1.0, v93
	v_add_f32_e32 v94, 1.0, v94
	v_add_f32_e32 v95, 1.0, v95
	v_add_f32_e32 v88, 1.0, v88
	v_add_f32_e32 v89, 1.0, v89
	v_add_f32_e32 v90, 1.0, v90
	v_add_f32_e32 v91, 1.0, v91
	v_add_f32_e32 v72, 1.0, v80
	v_add_f32_e32 v73, 1.0, v81
	v_add_f32_e32 v74, 1.0, v74
	v_add_f32_e32 v75, 1.0, v75
	v_rcp_f32_e32 v92, v92
	v_rcp_f32_e32 v93, v93
	v_rcp_f32_e32 v94, v94
	v_rcp_f32_e32 v95, v95
	v_rcp_f32_e32 v88, v88
	v_rcp_f32_e32 v89, v89
	v_rcp_f32_e32 v90, v90
	v_rcp_f32_e32 v91, v91
	v_rcp_f32_e32 v72, v72
	v_rcp_f32_e32 v73, v73
	v_rcp_f32_e32 v74, v74
	v_rcp_f32_e32 v75, v75
	v_add_f32_e32 v76, 1.0, v76
	v_add_f32_e32 v77, 1.0, v77
	v_add_f32_e32 v78, 1.0, v78
	v_add_f32_e32 v79, 1.0, v79
	v_rcp_f32_e32 v76, v76
	v_rcp_f32_e32 v77, v77
	v_rcp_f32_e32 v78, v78
	v_rcp_f32_e32 v79, v79
	v_add_f32_e32 v68, 1.0, v68
;     __device__ __forceinline__ void operator()(const f32x4 (&acc)[2][2][4][2], const Unit& u, int wr, int wc, int fr, int fq) const {
;     ...
;         for (int bj = 0; bj < 2; ++bj)
; #pragma unroll
;             for (int n = 0; n < 2; ++n) { const f32x4 bv = *(const f32x4*)(bias + col0 + bj * HALF + n * 16);
; #pragma unroll
;                 for (int ai = 0; ai < 2; ++ai)
; #pragma unroll
;                     for (int m = 0; m < 4; ++m) { f32x4 v = acc[ai][bj][m][n] + bv, o;
; #pragma unroll
;                         for (int e = 0; e < 4; ++e) { const float z = v[e];
;                             const float sg = __builtin_amdgcn_rcpf(1.0f + __builtin_amdgcn_exp2f(-1.4426950408889634f * z));
;                             if (MODE == 0) o[e] = __builtin_amdgcn_exp2f(-0.8750387749f * sg);
;                             else o[e] = sg; }
;                         __builtin_nontemporal_store(o, (f32x4*)(O + (size_t)(row0 + ai * HALF + m * 16) * 1536 + col0 + bj * HALF + n * 16)); } }
	v_add_f32_e32 v69, 1.0, v69
	v_add_f32_e32 v70, 1.0, v70
	v_add_f32_e32 v71, 1.0, v71
	v_rcp_f32_e32 v68, v68
	v_rcp_f32_e32 v69, v69
	v_rcp_f32_e32 v70, v70
	v_rcp_f32_e32 v71, v71
	v_add_f32_e32 v64, 1.0, v64
	v_add_f32_e32 v65, 1.0, v65
	v_add_f32_e32 v66, 1.0, v66
	v_add_f32_e32 v67, 1.0, v67
	v_rcp_f32_e32 v64, v64
	v_rcp_f32_e32 v65, v65
	v_rcp_f32_e32 v66, v66
	v_rcp_f32_e32 v67, v67
	flat_store_dwordx4 v[142:143], v[92:95] offset:64
	flat_store_dwordx4 v[140:141], v[88:91] offset:64
	flat_store_dwordx4 v[112:113], v[72:75] offset:64
	flat_store_dwordx4 v[108:109], v[76:79] offset:64
	flat_store_dwordx4 v[100:101], v[68:71] offset:64
	flat_store_dwordx4 v[96:97], v[64:67] offset:64
	s_nop 3
	v_mov_b64_e32 v[64:65], v[216:217]
	v_mov_b64_e32 v[66:67], v[218:219]
	v_add_f32_e32 v48, v48, v64
	v_add_f32_e32 v49, v49, v65
	v_add_f32_e32 v50, v50, v66
	v_add_f32_e32 v51, v51, v67
	v_add_f32_e32 v40, v40, v64
	v_add_f32_e32 v41, v41, v65
	v_add_f32_e32 v42, v42, v66
	v_add_f32_e32 v43, v43, v67
	v_mul_f32_e32 v48, 0xbfb8aa3b, v48
	v_mul_f32_e32 v49, 0xbfb8aa3b, v49
	v_mul_f32_e32 v50, 0xbfb8aa3b, v50
	v_mul_f32_e32 v51, 0xbfb8aa3b, v51
	v_mul_f32_e32 v40, 0xbfb8aa3b, v40
	v_mul_f32_e32 v41, 0xbfb8aa3b, v41
	v_mul_f32_e32 v42, 0xbfb8aa3b, v42
	v_mul_f32_e32 v43, 0xbfb8aa3b, v43
	v_exp_f32_e32 v48, v48
	v_exp_f32_e32 v49, v49
	v_exp_f32_e32 v50, v50
	v_exp_f32_e32 v51, v51
	v_exp_f32_e32 v40, v40
	v_exp_f32_e32 v41, v41
	v_exp_f32_e32 v42, v42
	v_exp_f32_e32 v43, v43
	v_add_f32_e32 v48, 1.0, v48
	v_add_f32_e32 v49, 1.0, v49
	v_add_f32_e32 v50, 1.0, v50
	v_add_f32_e32 v51, 1.0, v51
	v_add_f32_e32 v40, 1.0, v40
	v_add_f32_e32 v41, 1.0, v41
	v_add_f32_e32 v42, 1.0, v42
	v_add_f32_e32 v43, 1.0, v43
	v_rcp_f32_e32 v48, v48
	v_rcp_f32_e32 v49, v49
	v_rcp_f32_e32 v50, v50
	v_rcp_f32_e32 v51, v51
	v_rcp_f32_e32 v40, v40
	v_rcp_f32_e32 v41, v41
	v_rcp_f32_e32 v42, v42
	v_rcp_f32_e32 v43, v43
	v_add_f32_e32 v60, v60, v64
	v_add_f32_e32 v61, v61, v65
	v_add_f32_e32 v62, v62, v66
	v_add_f32_e32 v63, v63, v67
	v_add_f32_e32 v56, v56, v64
	v_add_f32_e32 v57, v57, v65
	v_add_f32_e32 v58, v58, v66
	v_add_f32_e32 v59, v59, v67
	flat_store_dwordx4 v[136:137], v[48:51] offset:512
	flat_store_dwordx4 v[116:117], v[40:43] offset:512
	v_mul_f32_e32 v60, 0xbfb8aa3b, v60
	v_add_f32_e32 v48, v52, v64
	v_add_f32_e32 v49, v53, v65
	v_add_f32_e32 v42, v54, v66
	v_add_f32_e32 v43, v55, v67
	v_mul_f32_e32 v61, 0xbfb8aa3b, v61
	v_mul_f32_e32 v62, 0xbfb8aa3b, v62
	v_mul_f32_e32 v63, 0xbfb8aa3b, v63
	v_mul_f32_e32 v56, 0xbfb8aa3b, v56
	v_mul_f32_e32 v57, 0xbfb8aa3b, v57
	v_mul_f32_e32 v58, 0xbfb8aa3b, v58
	v_mul_f32_e32 v59, 0xbfb8aa3b, v59
	v_mul_f32_e32 v48, 0xbfb8aa3b, v48
	v_mul_f32_e32 v49, 0xbfb8aa3b, v49
	v_mul_f32_e32 v42, 0xbfb8aa3b, v42
	v_mul_f32_e32 v43, 0xbfb8aa3b, v43
	v_add_f32_e32 v44, v44, v64
	v_add_f32_e32 v45, v45, v65
	v_add_f32_e32 v46, v46, v66
	v_add_f32_e32 v47, v47, v67
	v_exp_f32_e32 v60, v60
	v_exp_f32_e32 v61, v61
	v_exp_f32_e32 v62, v62
	v_exp_f32_e32 v63, v63
	v_exp_f32_e32 v56, v56
	v_exp_f32_e32 v57, v57
	v_exp_f32_e32 v58, v58
	v_exp_f32_e32 v59, v59
	v_exp_f32_e32 v48, v48
	v_exp_f32_e32 v49, v49
	v_exp_f32_e32 v42, v42
	v_exp_f32_e32 v43, v43
	v_mul_f32_e32 v44, 0xbfb8aa3b, v44
	v_mul_f32_e32 v45, 0xbfb8aa3b, v45
	v_mul_f32_e32 v46, 0xbfb8aa3b, v46
	v_mul_f32_e32 v47, 0xbfb8aa3b, v47
	v_add_f32_e32 v36, v36, v64
	v_add_f32_e32 v37, v37, v65
	v_add_f32_e32 v38, v38, v66
	v_add_f32_e32 v39, v39, v67
	v_exp_f32_e32 v44, v44
	v_exp_f32_e32 v45, v45
	v_exp_f32_e32 v46, v46
	v_exp_f32_e32 v47, v47
	v_mul_f32_e32 v36, 0xbfb8aa3b, v36
	v_mul_f32_e32 v37, 0xbfb8aa3b, v37
	v_mul_f32_e32 v38, 0xbfb8aa3b, v38
	v_mul_f32_e32 v39, 0xbfb8aa3b, v39
	v_add_f32_e32 v32, v32, v64
	v_add_f32_e32 v33, v33, v65
	v_add_f32_e32 v34, v34, v66
	v_add_f32_e32 v35, v35, v67
	v_exp_f32_e32 v36, v36
	v_exp_f32_e32 v37, v37
	v_exp_f32_e32 v38, v38
	v_exp_f32_e32 v39, v39
	v_mul_f32_e32 v32, 0xbfb8aa3b, v32
	v_mul_f32_e32 v33, 0xbfb8aa3b, v33
	v_mul_f32_e32 v34, 0xbfb8aa3b, v34
	v_mul_f32_e32 v35, 0xbfb8aa3b, v35
	v_exp_f32_e32 v32, v32
	v_exp_f32_e32 v33, v33
	v_exp_f32_e32 v34, v34
	v_exp_f32_e32 v35, v35
	v_add_f32_e32 v60, 1.0, v60
	v_add_f32_e32 v61, 1.0, v61
	v_add_f32_e32 v62, 1.0, v62
	v_add_f32_e32 v63, 1.0, v63
	v_add_f32_e32 v56, 1.0, v56
	v_add_f32_e32 v57, 1.0, v57
	v_add_f32_e32 v58, 1.0, v58
	v_add_f32_e32 v59, 1.0, v59
	v_add_f32_e32 v40, 1.0, v48
	v_add_f32_e32 v41, 1.0, v49
	v_add_f32_e32 v42, 1.0, v42
	v_add_f32_e32 v43, 1.0, v43
	v_rcp_f32_e32 v60, v60
	v_rcp_f32_e32 v61, v61
	v_rcp_f32_e32 v62, v62
	v_rcp_f32_e32 v63, v63
	v_rcp_f32_e32 v56, v56
	v_rcp_f32_e32 v57, v57
	v_rcp_f32_e32 v58, v58
	v_rcp_f32_e32 v59, v59
	v_rcp_f32_e32 v40, v40
	v_rcp_f32_e32 v41, v41
	v_rcp_f32_e32 v42, v42
	v_rcp_f32_e32 v43, v43
	v_add_f32_e32 v44, 1.0, v44
	v_add_f32_e32 v45, 1.0, v45
	v_add_f32_e32 v46, 1.0, v46
	v_add_f32_e32 v47, 1.0, v47
	v_rcp_f32_e32 v44, v44
	v_rcp_f32_e32 v45, v45
	v_rcp_f32_e32 v46, v46
	v_rcp_f32_e32 v47, v47
	v_add_f32_e32 v36, 1.0, v36
	v_add_f32_e32 v37, 1.0, v37
	v_add_f32_e32 v38, 1.0, v38
	v_add_f32_e32 v39, 1.0, v39
	v_rcp_f32_e32 v36, v36
	v_rcp_f32_e32 v37, v37
	v_rcp_f32_e32 v38, v38
	v_rcp_f32_e32 v39, v39
	v_add_f32_e32 v32, 1.0, v32
	v_add_f32_e32 v33, 1.0, v33
	v_add_f32_e32 v34, 1.0, v34
	v_add_f32_e32 v35, 1.0, v35
	v_rcp_f32_e32 v32, v32
	v_rcp_f32_e32 v33, v33
;     __device__ __forceinline__ void operator()(const f32x4 (&acc)[2][2][4][2], const Unit& u, int wr, int wc, int fr, int fq) const {
;     ...
;         for (int bj = 0; bj < 2; ++bj)
; #pragma unroll
;             for (int n = 0; n < 2; ++n) { const f32x4 bv = *(const f32x4*)(bias + col0 + bj * HALF + n * 16);
; #pragma unroll
;                 for (int ai = 0; ai < 2; ++ai)
; #pragma unroll
;                     for (int m = 0; m < 4; ++m) { f32x4 v = acc[ai][bj][m][n] + bv, o;
; #pragma unroll
;                         for (int e = 0; e < 4; ++e) { const float z = v[e];
;                             const float sg = __builtin_amdgcn_rcpf(1.0f + __builtin_amdgcn_exp2f(-1.4426950408889634f * z));
;                             if (MODE == 0) o[e] = __builtin_amdgcn_exp2f(-0.8750387749f * sg);
;                             else o[e] = sg; }
;                         __builtin_nontemporal_store(o, (f32x4*)(O + (size_t)(row0 + ai * HALF + m * 16) * 1536 + col0 + bj * HALF + n * 16)); } }
	v_rcp_f32_e32 v34, v34
	v_rcp_f32_e32 v35, v35
	flat_store_dwordx4 v[142:143], v[60:63] offset:512
	flat_store_dwordx4 v[140:141], v[56:59] offset:512
	flat_store_dwordx4 v[112:113], v[40:43] offset:512
	flat_store_dwordx4 v[108:109], v[44:47] offset:512
	flat_store_dwordx4 v[100:101], v[36:39] offset:512
	flat_store_dwordx4 v[96:97], v[32:35] offset:512
	s_nop 3
	v_mov_b64_e32 v[32:33], v[220:221]
	v_mov_b64_e32 v[34:35], v[222:223]
	v_add_f32_e32 v16, v16, v32
	v_add_f32_e32 v17, v17, v33
	v_add_f32_e32 v18, v18, v34
	v_add_f32_e32 v19, v19, v35
	v_add_f32_e32 v8, v8, v32
	v_add_f32_e32 v9, v9, v33
	v_add_f32_e32 v10, v10, v34
	v_add_f32_e32 v11, v11, v35
	v_mul_f32_e32 v16, 0xbfb8aa3b, v16
	v_mul_f32_e32 v17, 0xbfb8aa3b, v17
	v_mul_f32_e32 v18, 0xbfb8aa3b, v18
	v_mul_f32_e32 v19, 0xbfb8aa3b, v19
	v_mul_f32_e32 v8, 0xbfb8aa3b, v8
	v_mul_f32_e32 v9, 0xbfb8aa3b, v9
	v_mul_f32_e32 v10, 0xbfb8aa3b, v10
	v_mul_f32_e32 v11, 0xbfb8aa3b, v11
	v_exp_f32_e32 v16, v16
	v_exp_f32_e32 v17, v17
	v_exp_f32_e32 v18, v18
	v_exp_f32_e32 v19, v19
	v_exp_f32_e32 v8, v8
	v_exp_f32_e32 v9, v9
	v_exp_f32_e32 v10, v10
	v_exp_f32_e32 v11, v11
	v_add_f32_e32 v16, 1.0, v16
	v_add_f32_e32 v17, 1.0, v17
	v_add_f32_e32 v18, 1.0, v18
	v_add_f32_e32 v19, 1.0, v19
	v_add_f32_e32 v8, 1.0, v8
	v_add_f32_e32 v9, 1.0, v9
	v_add_f32_e32 v10, 1.0, v10
	v_add_f32_e32 v11, 1.0, v11
	v_rcp_f32_e32 v16, v16
	v_rcp_f32_e32 v17, v17
	v_rcp_f32_e32 v18, v18
	v_rcp_f32_e32 v19, v19
	v_rcp_f32_e32 v8, v8
	v_rcp_f32_e32 v9, v9
	v_rcp_f32_e32 v10, v10
	v_rcp_f32_e32 v11, v11
	v_add_f32_e32 v28, v28, v32
	v_add_f32_e32 v29, v29, v33
	v_add_f32_e32 v30, v30, v34
	v_add_f32_e32 v31, v31, v35
	v_add_f32_e32 v24, v24, v32
	v_add_f32_e32 v25, v25, v33
	v_add_f32_e32 v26, v26, v34
	v_add_f32_e32 v27, v27, v35
	flat_store_dwordx4 v[136:137], v[16:19] offset:576
	flat_store_dwordx4 v[116:117], v[8:11] offset:576
	v_mul_f32_e32 v28, 0xbfb8aa3b, v28
	v_add_f32_e32 v16, v20, v32
	v_add_f32_e32 v17, v21, v33
	v_add_f32_e32 v10, v22, v34
	v_add_f32_e32 v11, v23, v35
	v_mul_f32_e32 v29, 0xbfb8aa3b, v29
	v_mul_f32_e32 v30, 0xbfb8aa3b, v30
	v_mul_f32_e32 v31, 0xbfb8aa3b, v31
	v_mul_f32_e32 v24, 0xbfb8aa3b, v24
	v_mul_f32_e32 v25, 0xbfb8aa3b, v25
	v_mul_f32_e32 v26, 0xbfb8aa3b, v26
	v_mul_f32_e32 v27, 0xbfb8aa3b, v27
	v_mul_f32_e32 v16, 0xbfb8aa3b, v16
	v_mul_f32_e32 v17, 0xbfb8aa3b, v17
	v_mul_f32_e32 v10, 0xbfb8aa3b, v10
	v_mul_f32_e32 v11, 0xbfb8aa3b, v11
	v_add_f32_e32 v12, v12, v32
	v_add_f32_e32 v13, v13, v33
	v_add_f32_e32 v14, v14, v34
	v_add_f32_e32 v15, v15, v35
	v_exp_f32_e32 v28, v28
	v_exp_f32_e32 v29, v29
	v_exp_f32_e32 v30, v30
	v_exp_f32_e32 v31, v31
	v_exp_f32_e32 v24, v24
	v_exp_f32_e32 v25, v25
	v_exp_f32_e32 v26, v26
	v_exp_f32_e32 v27, v27
	v_exp_f32_e32 v16, v16
	v_exp_f32_e32 v17, v17
	v_exp_f32_e32 v10, v10
	v_exp_f32_e32 v11, v11
	v_mul_f32_e32 v12, 0xbfb8aa3b, v12
	v_mul_f32_e32 v13, 0xbfb8aa3b, v13
	v_mul_f32_e32 v14, 0xbfb8aa3b, v14
	v_mul_f32_e32 v15, 0xbfb8aa3b, v15
	v_add_f32_e32 v4, v4, v32
	v_add_f32_e32 v5, v5, v33
	v_add_f32_e32 v6, v6, v34
	v_add_f32_e32 v7, v7, v35
	v_exp_f32_e32 v12, v12
	v_exp_f32_e32 v13, v13
	v_exp_f32_e32 v14, v14
	v_exp_f32_e32 v15, v15
	v_mul_f32_e32 v4, 0xbfb8aa3b, v4
	v_mul_f32_e32 v5, 0xbfb8aa3b, v5
	v_mul_f32_e32 v6, 0xbfb8aa3b, v6
	v_mul_f32_e32 v7, 0xbfb8aa3b, v7
	v_add_f32_e32 v0, v0, v32
	v_add_f32_e32 v1, v1, v33
	v_add_f32_e32 v2, v2, v34
	v_add_f32_e32 v3, v3, v35
	v_exp_f32_e32 v4, v4
	v_exp_f32_e32 v5, v5
	v_exp_f32_e32 v6, v6
	v_exp_f32_e32 v7, v7
	v_mul_f32_e32 v0, 0xbfb8aa3b, v0
	v_mul_f32_e32 v1, 0xbfb8aa3b, v1
	v_mul_f32_e32 v2, 0xbfb8aa3b, v2
	v_mul_f32_e32 v3, 0xbfb8aa3b, v3
	v_exp_f32_e32 v0, v0
	v_exp_f32_e32 v1, v1
	v_exp_f32_e32 v2, v2
	v_exp_f32_e32 v3, v3
	v_add_f32_e32 v28, 1.0, v28
	v_add_f32_e32 v29, 1.0, v29
	v_add_f32_e32 v30, 1.0, v30
	v_add_f32_e32 v31, 1.0, v31
	v_add_f32_e32 v24, 1.0, v24
	v_add_f32_e32 v25, 1.0, v25
	v_add_f32_e32 v26, 1.0, v26
	v_add_f32_e32 v27, 1.0, v27
	v_add_f32_e32 v8, 1.0, v16
	v_add_f32_e32 v9, 1.0, v17
	v_add_f32_e32 v10, 1.0, v10
	v_add_f32_e32 v11, 1.0, v11
	v_rcp_f32_e32 v28, v28
	v_rcp_f32_e32 v29, v29
	v_rcp_f32_e32 v30, v30
	v_rcp_f32_e32 v31, v31
	v_rcp_f32_e32 v24, v24
	v_rcp_f32_e32 v25, v25
	v_rcp_f32_e32 v26, v26
	v_rcp_f32_e32 v27, v27
	v_rcp_f32_e32 v8, v8
	v_rcp_f32_e32 v9, v9
	v_rcp_f32_e32 v10, v10
	v_rcp_f32_e32 v11, v11
	v_add_f32_e32 v12, 1.0, v12
	v_add_f32_e32 v13, 1.0, v13
	v_add_f32_e32 v14, 1.0, v14
	v_add_f32_e32 v15, 1.0, v15
	v_rcp_f32_e32 v12, v12
	v_rcp_f32_e32 v13, v13
	v_rcp_f32_e32 v14, v14
	v_rcp_f32_e32 v15, v15
	v_add_f32_e32 v4, 1.0, v4
	v_add_f32_e32 v5, 1.0, v5
	v_add_f32_e32 v6, 1.0, v6
	v_add_f32_e32 v7, 1.0, v7
	v_rcp_f32_e32 v4, v4
	v_rcp_f32_e32 v5, v5
	v_rcp_f32_e32 v6, v6
	v_rcp_f32_e32 v7, v7
	v_add_f32_e32 v0, 1.0, v0
	v_add_f32_e32 v1, 1.0, v1
	v_add_f32_e32 v2, 1.0, v2
	v_add_f32_e32 v3, 1.0, v3
	v_rcp_f32_e32 v0, v0
	v_rcp_f32_e32 v1, v1
	v_rcp_f32_e32 v2, v2
	v_rcp_f32_e32 v3, v3
	flat_store_dwordx4 v[142:143], v[28:31] offset:576
	flat_store_dwordx4 v[140:141], v[24:27] offset:576
	flat_store_dwordx4 v[112:113], v[8:11] offset:576
	flat_store_dwordx4 v[108:109], v[12:15] offset:576
	flat_store_dwordx4 v[100:101], v[4:7] offset:576
	flat_store_dwordx4 v[96:97], v[0:3] offset:576
	s_cbranch_vccnz .LBB0_392
	s_andn2_b64 vcc, exec, s[2:3]
	s_cbranch_vccnz .LBB0_391
	s_barrier
	s_branch .LBB0_391
